# GEMM K-loops: first iteration peeled with C=0 on each accumulator's first MFMA, the 128 v_mov zeroing per output tile removed
# speedup vs baseline: 1.0113x; 1.0113x over previous
; #define PG8_STAGE(bufoff, gbase, voff) do { _Pragma("unroll") for (int _i = 0; _i < 2; ++_i) \
;         __builtin_amdgcn_global_load_lds((const unsigned*)((const char*)(gbase) + (voff)[_i]), (PG8_LAS unsigned*)(lds + (bufoff) + ldsw + _i * 8192), 16, 0, 0); } while (0)
; #define PG8_LDA(dst, b, h) do { _Pragma("unroll") for (int m = 0; m < 4; ++m) _Pragma("unroll") for (int k = 0; k < 2; ++k) dst[m][k] = *(const PG8_LAS bf16x8*)(lds + PG8_SA(b, h) + aoff + m * 2048 + k * 1024); } while (0)
; #define PG8_LDB(dst, b, h) do { _Pragma("unroll") for (int n = 0; n < 2; ++n) _Pragma("unroll") for (int k = 0; k < 2; ++k) dst[n][k] = *(const PG8_LAS bf16x8*)(lds + PG8_SB(b, h) + boff + n * 2048 + k * 1024); } while (0)
; template <class Epi, class Sched, bool ALIGN_EPI = false, bool SP2 = false>
; __device__ __forceinline__ void gemm_phase(PG8_LAS unsigned char* lds, const Gemm g, const Sched& S, const Epi& E) {
;     ...
;         const bool has_next = S.next(ui + 1, nxt);
;         const char* nA = has_next ? (const char*)g.A + (size_t)nxt.pm * tstep : cA; const char* nB = has_next ? (const char*)g.Bt + (size_t)nxt.pn * tstep : cB;
;         for (int t = 0; t < nt; t += 2) {
;             const bool last = (t == nt - 2);
;             const char* a1 = cA + (size_t)(t + 1) * kstep;
;             const char* a2 = last ? nA : cA + (size_t)(t + 2) * kstep; const char* b2 = last ? nB : cB + (size_t)(t + 2) * kstep;
;             const char* a3 = a2 + kstep; const char* b3 = b2 + kstep;
;             if (last && has_next) S.a_ready(nxt);
;             if constexpr (SP2) {
;             PG8_LDB(B0, 0, 0); PG8_LDB(B1, 0, 1); PG8_SCHED; PG8_LDA(At, 0, 0); PG8_STAGE(PG8_SA(1, 1), a1 + hstep, voffA);
;             PG8_WAIT_V(8); PG8_WAIT_L(0); PG8_BAR; PG8_MMA(0, 0, At, B0); PG8_MMA(0, 1, At, B1); PG8_BAR; PG8_SCHED;
;             PG8_LDA(At, 0, 1); PG8_STAGE(PG8_SB(0, 0), b2, voffB); PG8_STAGE(PG8_SB(0, 1), b2 + hstep, voffB); PG8_STAGE(PG8_SA(0, 0), a2, voffA);
;             PG8_WAIT_V(8); PG8_WAIT_L(0); PG8_BAR; PG8_MMA(1, 0, At, B0); PG8_MMA(1, 1, At, B1); PG8_BAR; PG8_SCHED;
;     ...
;         for (int a = 0; a < 2; ++a)
; #pragma unroll
;             for (int b = 0; b < 2; ++b)
; #pragma unroll
;                 for (int m = 0; m < 4; ++m)
; #pragma unroll
;                     for (int n = 0; n < 2; ++n) acc[a][b][m][n] = (f32x4){0.f, 0.f, 0.f, 0.f};
.LBB0_43:
	s_ashr_i32 s47, s46, 31
	s_lshl_b64 s[24:25], s[46:47], 19
	s_add_u32 s48, s26, s24
	s_addc_u32 s49, s27, s25
	s_and_b64 s[24:25], s[40:41], exec
	s_cselect_b32 s1, s49, s61
	s_cselect_b32 s12, s48, s60
	s_ashr_i32 s3, s2, 31
	s_lshl_b64 s[24:25], s[2:3], 19
	s_add_u32 s56, s23, s24
	s_addc_u32 s57, s29, s25
	s_and_b64 s[24:25], s[40:41], exec
	s_cselect_b32 s3, s57, s63
	s_cselect_b32 s22, s56, s62
	s_add_u32 s60, s60, 0x40080
	s_addc_u32 s61, s61, 0
	s_add_u32 s33, s62, 0x100
	s_addc_u32 s44, s63, 0
	s_mov_b32 s45, -2
	s_add_u32 s24, s60, 0xfffc0080
	s_addc_u32 s25, s61, -1
	s_add_i32 s47, 0, 0x10000
	s_cmp_eq_u32 s45, 12
	s_cselect_b32 s65, s1, s25
	s_cselect_b32 s64, s12, s24
	v_add_u32_e32 v150, s47, v153
	s_cselect_b32 s63, s3, s44
	s_cselect_b32 s62, s22, s33
	s_add_i32 s50, 0, 0x14000
	ds_read_b128 v[146:149], v150
	ds_read_b128 v[156:159], v150 offset:1024
	ds_read_b128 v[160:163], v150 offset:2048
	ds_read_b128 v[164:167], v150 offset:3072
	v_add_u32_e32 v150, s50, v153
	ds_read_b128 v[168:171], v150
	ds_read_b128 v[192:195], v150 offset:1024
	ds_read_b128 v[196:199], v150 offset:2048
	ds_read_b128 v[200:203], v150 offset:3072
	v_lshl_add_u64 v[150:151], s[60:61], 0, v[142:143]
	s_add_i32 m0, s68, 0xc000
	ds_read_b128 v[204:207], v155
	ds_read_b128 v[208:211], v155 offset:1024
	ds_read_b128 v[212:215], v155 offset:2048
	ds_read_b128 v[216:219], v155 offset:3072
	ds_read_b128 v[220:223], v155 offset:4096
	ds_read_b128 v[224:227], v155 offset:5120
	ds_read_b128 v[228:231], v155 offset:6144
	ds_read_b128 v[232:235], v155 offset:7168
	global_load_lds_dwordx4 v[150:151], off
	v_lshl_add_u64 v[150:151], s[60:61], 0, v[144:145]
	s_add_i32 m0, s68, 0xe000
	s_nop 0
	global_load_lds_dwordx4 v[150:151], off
	s_waitcnt vmcnt(8)
	s_waitcnt lgkmcnt(0)
	s_barrier
	s_setprio 1
	s_waitcnt lgkmcnt(0)
	v_mfma_f32_16x16x32_bf16 v[124:127], v[146:149], v[204:207], 0
	v_mfma_f32_16x16x32_bf16 v[120:123], v[160:163], v[204:207], 0
	v_mfma_f32_16x16x32_bf16 v[108:111], v[146:149], v[212:215], 0
	v_mfma_f32_16x16x32_bf16 v[104:107], v[160:163], v[212:215], 0
	v_mfma_f32_16x16x32_bf16 v[92:95], v[146:149], v[220:223], 0
	v_mfma_f32_16x16x32_bf16 v[88:91], v[160:163], v[220:223], 0
	v_mfma_f32_16x16x32_bf16 v[76:79], v[146:149], v[228:231], 0
	v_mfma_f32_16x16x32_bf16 v[72:75], v[160:163], v[228:231], 0
	v_mfma_f32_16x16x32_bf16 v[124:127], v[156:159], v[208:211], v[124:127]
	v_mfma_f32_16x16x32_bf16 v[120:123], v[164:167], v[208:211], v[120:123]
	v_mfma_f32_16x16x32_bf16 v[108:111], v[156:159], v[216:219], v[108:111]
	v_mfma_f32_16x16x32_bf16 v[104:107], v[164:167], v[216:219], v[104:107]
	v_mfma_f32_16x16x32_bf16 v[92:95], v[156:159], v[224:227], v[92:95]
	v_mfma_f32_16x16x32_bf16 v[88:91], v[164:167], v[224:227], v[88:91]
	v_mfma_f32_16x16x32_bf16 v[76:79], v[156:159], v[232:235], v[76:79]
	v_mfma_f32_16x16x32_bf16 v[72:75], v[164:167], v[232:235], v[72:75]
	s_setprio 0
	s_setprio 1
	v_mfma_f32_16x16x32_bf16 v[116:119], v[168:171], v[204:207], 0
	v_mfma_f32_16x16x32_bf16 v[112:115], v[196:199], v[204:207], 0
	v_mfma_f32_16x16x32_bf16 v[100:103], v[168:171], v[212:215], 0
	v_mfma_f32_16x16x32_bf16 v[96:99], v[196:199], v[212:215], 0
	v_mfma_f32_16x16x32_bf16 v[84:87], v[168:171], v[220:223], 0
	v_mfma_f32_16x16x32_bf16 v[80:83], v[196:199], v[220:223], 0
	v_mfma_f32_16x16x32_bf16 v[68:71], v[168:171], v[228:231], 0
	v_mfma_f32_16x16x32_bf16 v[64:67], v[196:199], v[228:231], 0
	v_mfma_f32_16x16x32_bf16 v[116:119], v[192:195], v[208:211], v[116:119]
	v_mfma_f32_16x16x32_bf16 v[112:115], v[200:203], v[208:211], v[112:115]
	v_mfma_f32_16x16x32_bf16 v[100:103], v[192:195], v[216:219], v[100:103]
	v_mfma_f32_16x16x32_bf16 v[96:99], v[200:203], v[216:219], v[96:99]
	v_mfma_f32_16x16x32_bf16 v[84:87], v[192:195], v[224:227], v[84:87]
	v_mfma_f32_16x16x32_bf16 v[80:83], v[200:203], v[224:227], v[80:83]
	v_mfma_f32_16x16x32_bf16 v[68:71], v[192:195], v[232:235], v[68:71]
	v_mfma_f32_16x16x32_bf16 v[64:67], v[200:203], v[232:235], v[64:67]
	s_setprio 0
	s_barrier
	s_add_i32 s24, s47, s66
	v_lshl_add_u64 v[150:151], s[62:63], 0, v[132:133]
	s_mov_b32 m0, s24
	ds_read_b128 v[204:207], v155 offset:16384
	ds_read_b128 v[208:211], v155 offset:17408
	ds_read_b128 v[212:215], v155 offset:18432
	ds_read_b128 v[216:219], v155 offset:19456
	ds_read_b128 v[220:223], v155 offset:20480
	ds_read_b128 v[224:227], v155 offset:21504
	ds_read_b128 v[228:231], v155 offset:22528
	ds_read_b128 v[232:235], v155 offset:23552
	global_load_lds_dwordx4 v[150:151], off
	s_add_i32 m0, s24, 0x2000
	s_add_u32 s24, s62, 0x40000
	v_lshl_add_u64 v[236:237], s[62:63], 0, v[128:129]
	s_addc_u32 s25, s63, 0
	s_add_i32 s47, s50, s66
	global_load_lds_dwordx4 v[236:237], off
	v_lshl_add_u64 v[238:239], s[24:25], 0, v[132:133]
	s_mov_b32 m0, s47
	v_lshl_add_u64 v[240:241], s[64:65], 0, v[130:131]
	global_load_lds_dwordx4 v[238:239], off
	v_lshl_add_u64 v[238:239], s[24:25], 0, v[128:129]
	s_add_i32 m0, s47, 0x2000
	s_nop 0
	global_load_lds_dwordx4 v[238:239], off
	v_lshl_add_u64 v[238:239], s[64:65], 0, v[140:141]
	s_mov_b32 m0, s68
	s_nop 0
	global_load_lds_dwordx4 v[238:239], off
	s_mov_b32 m0, s69
	s_nop 0
	global_load_lds_dwordx4 v[240:241], off
	s_waitcnt vmcnt(8)
	s_waitcnt lgkmcnt(0)
	s_barrier
; #define PG8_STAGE(bufoff, gbase, voff) do { _Pragma("unroll") for (int _i = 0; _i < 2; ++_i) \
;         __builtin_amdgcn_global_load_lds((const unsigned*)((const char*)(gbase) + (voff)[_i]), (PG8_LAS unsigned*)(lds + (bufoff) + ldsw + _i * 8192), 16, 0, 0); } while (0)
; #define PG8_LDA(dst, b, h) do { _Pragma("unroll") for (int m = 0; m < 4; ++m) _Pragma("unroll") for (int k = 0; k < 2; ++k) dst[m][k] = *(const PG8_LAS bf16x8*)(lds + PG8_SA(b, h) + aoff + m * 2048 + k * 1024); } while (0)
; #define PG8_LDB(dst, b, h) do { _Pragma("unroll") for (int n = 0; n < 2; ++n) _Pragma("unroll") for (int k = 0; k < 2; ++k) dst[n][k] = *(const PG8_LAS bf16x8*)(lds + PG8_SB(b, h) + boff + n * 2048 + k * 1024); } while (0)
; #define PG8_MMA(ai, bj, At, Bt) do { __builtin_amdgcn_s_setprio(1); _Pragma("unroll") for (int m = 0; m < 4; ++m) _Pragma("unroll") for (int n = 0; n < 2; ++n) _Pragma("unroll") for (int k = 0; k < 2; ++k) \
;         acc[ai][bj][m][n] = __builtin_amdgcn_mfma_f32_16x16x32_bf16(Bt[n][k], At[m][k], acc[ai][bj][m][n], 0, 0, 0); __builtin_amdgcn_s_setprio(0); } while (0)
; #define PG8_WAIT_V(n) asm volatile("s_waitcnt vmcnt(" #n ")" ::: "memory")
; #define PG8_WAIT_L(n) asm volatile("s_waitcnt lgkmcnt(" #n ")" ::: "memory")
; #define PG8_BAR __builtin_amdgcn_s_barrier()
; #define PG8_SCHED __builtin_amdgcn_sched_barrier(0)
; template <class Epi, class Sched, bool ALIGN_EPI = false, bool SP2 = false>
; __device__ __forceinline__ void gemm_phase(PG8_LAS unsigned char* lds, const Gemm g, const Sched& S, const Epi& E) {
;     ...
;             PG8_WAIT_V(8); PG8_WAIT_L(0); PG8_BAR; PG8_MMA(1, 0, At, B0); PG8_MMA(1, 1, At, B1); PG8_BAR; PG8_SCHED;
;             PG8_LDB(B0, 1, 0); PG8_LDB(B1, 1, 1); PG8_SCHED; PG8_LDA(At, 1, 0); PG8_STAGE(PG8_SA(0, 1), a2 + hstep, voffA);
;             PG8_WAIT_V(8); PG8_WAIT_L(0); PG8_BAR; PG8_MMA(0, 0, At, B0); PG8_MMA(0, 1, At, B1); PG8_BAR; PG8_SCHED;
;             PG8_LDA(At, 1, 1); PG8_STAGE(PG8_SB(1, 0), b3, voffB); PG8_STAGE(PG8_SB(1, 1), b3 + hstep, voffB); PG8_STAGE(PG8_SA(1, 0), a3, voffA);
;             PG8_WAIT_V(8); PG8_WAIT_L(0); PG8_BAR; PG8_MMA(1, 0, At, B0); PG8_MMA(1, 1, At, B1); PG8_BAR; PG8_SCHED;
	s_setprio 1
	s_waitcnt lgkmcnt(0)
	v_mfma_f32_16x16x32_bf16 v[60:63], v[146:149], v[204:207], 0
	v_mfma_f32_16x16x32_bf16 v[56:59], v[160:163], v[204:207], 0
	v_mfma_f32_16x16x32_bf16 v[44:47], v[146:149], v[212:215], 0
	v_mfma_f32_16x16x32_bf16 v[40:43], v[160:163], v[212:215], 0
	v_mfma_f32_16x16x32_bf16 v[28:31], v[146:149], v[220:223], 0
	v_mfma_f32_16x16x32_bf16 v[24:27], v[160:163], v[220:223], 0
	v_mfma_f32_16x16x32_bf16 v[12:15], v[146:149], v[228:231], 0
	v_mfma_f32_16x16x32_bf16 v[8:11], v[160:163], v[228:231], 0
	v_mfma_f32_16x16x32_bf16 v[60:63], v[156:159], v[208:211], v[60:63]
	v_mfma_f32_16x16x32_bf16 v[56:59], v[164:167], v[208:211], v[56:59]
	v_mfma_f32_16x16x32_bf16 v[44:47], v[156:159], v[216:219], v[44:47]
	v_mfma_f32_16x16x32_bf16 v[40:43], v[164:167], v[216:219], v[40:43]
	v_mfma_f32_16x16x32_bf16 v[28:31], v[156:159], v[224:227], v[28:31]
	v_mfma_f32_16x16x32_bf16 v[24:27], v[164:167], v[224:227], v[24:27]
	v_mfma_f32_16x16x32_bf16 v[12:15], v[156:159], v[232:235], v[12:15]
	v_mfma_f32_16x16x32_bf16 v[8:11], v[164:167], v[232:235], v[8:11]
	s_setprio 0
	s_setprio 1
	v_mfma_f32_16x16x32_bf16 v[52:55], v[168:171], v[204:207], 0
	v_mfma_f32_16x16x32_bf16 v[48:51], v[196:199], v[204:207], 0
	v_mfma_f32_16x16x32_bf16 v[36:39], v[168:171], v[212:215], 0
	v_mfma_f32_16x16x32_bf16 v[32:35], v[196:199], v[212:215], 0
	v_mfma_f32_16x16x32_bf16 v[20:23], v[168:171], v[220:223], 0
	v_mfma_f32_16x16x32_bf16 v[16:19], v[196:199], v[220:223], 0
	v_mfma_f32_16x16x32_bf16 v[4:7], v[168:171], v[228:231], 0
	v_mfma_f32_16x16x32_bf16 v[0:3], v[196:199], v[228:231], 0
	v_mfma_f32_16x16x32_bf16 v[52:55], v[192:195], v[208:211], v[52:55]
	v_mfma_f32_16x16x32_bf16 v[48:51], v[200:203], v[208:211], v[48:51]
	v_mfma_f32_16x16x32_bf16 v[36:39], v[192:195], v[216:219], v[36:39]
	v_mfma_f32_16x16x32_bf16 v[32:35], v[200:203], v[216:219], v[32:35]
	v_mfma_f32_16x16x32_bf16 v[20:23], v[192:195], v[224:227], v[20:23]
	v_mfma_f32_16x16x32_bf16 v[16:19], v[200:203], v[224:227], v[16:19]
	v_mfma_f32_16x16x32_bf16 v[4:7], v[192:195], v[232:235], v[4:7]
	v_mfma_f32_16x16x32_bf16 v[0:3], v[200:203], v[232:235], v[0:3]
	s_setprio 0
	s_barrier
	s_add_i32 s47, 0, 0x18000
	s_add_i32 s50, 0, 0x1c000
	v_add_u32_e32 v164, s47, v153
	v_add_u32_e32 v184, s50, v153
	ds_read_b128 v[146:149], v164
	ds_read_b128 v[156:159], v164 offset:1024
	ds_read_b128 v[160:163], v164 offset:2048
	ds_read_b128 v[164:167], v164 offset:3072
	ds_read_b128 v[168:171], v184
	ds_read_b128 v[192:195], v184 offset:1024
	ds_read_b128 v[196:199], v184 offset:2048
	ds_read_b128 v[200:203], v184 offset:3072
	s_add_u32 s24, s64, 0x40000
	s_addc_u32 s25, s65, 0
	s_mov_b32 m0, s71
	v_lshl_add_u64 v[242:243], s[24:25], 0, v[140:141]
	ds_read_b128 v[204:207], v155 offset:32768
	ds_read_b128 v[208:211], v155 offset:33792
	ds_read_b128 v[212:215], v155 offset:34816
	ds_read_b128 v[216:219], v155 offset:35840
	ds_read_b128 v[220:223], v155 offset:36864
	ds_read_b128 v[224:227], v155 offset:37888
	ds_read_b128 v[228:231], v155 offset:38912
	ds_read_b128 v[232:235], v155 offset:39936
	global_load_lds_dwordx4 v[242:243], off
	v_lshl_add_u64 v[242:243], s[24:25], 0, v[130:131]
	s_mov_b32 m0, s87
	s_nop 0
	global_load_lds_dwordx4 v[242:243], off
	s_waitcnt vmcnt(8)
	s_waitcnt lgkmcnt(0)
	s_barrier
	s_setprio 1
	s_waitcnt lgkmcnt(0)
	v_mfma_f32_16x16x32_bf16 v[124:127], v[146:149], v[204:207], v[124:127]
	v_mfma_f32_16x16x32_bf16 v[120:123], v[160:163], v[204:207], v[120:123]
	v_mfma_f32_16x16x32_bf16 v[108:111], v[146:149], v[212:215], v[108:111]
	v_mfma_f32_16x16x32_bf16 v[104:107], v[160:163], v[212:215], v[104:107]
	v_mfma_f32_16x16x32_bf16 v[92:95], v[146:149], v[220:223], v[92:95]
	v_mfma_f32_16x16x32_bf16 v[88:91], v[160:163], v[220:223], v[88:91]
	v_mfma_f32_16x16x32_bf16 v[76:79], v[146:149], v[228:231], v[76:79]
	v_mfma_f32_16x16x32_bf16 v[72:75], v[160:163], v[228:231], v[72:75]
	v_mfma_f32_16x16x32_bf16 v[124:127], v[156:159], v[208:211], v[124:127]
	v_mfma_f32_16x16x32_bf16 v[120:123], v[164:167], v[208:211], v[120:123]
	v_mfma_f32_16x16x32_bf16 v[108:111], v[156:159], v[216:219], v[108:111]
	v_mfma_f32_16x16x32_bf16 v[104:107], v[164:167], v[216:219], v[104:107]
	v_mfma_f32_16x16x32_bf16 v[92:95], v[156:159], v[224:227], v[92:95]
	v_mfma_f32_16x16x32_bf16 v[88:91], v[164:167], v[224:227], v[88:91]
	v_mfma_f32_16x16x32_bf16 v[76:79], v[156:159], v[232:235], v[76:79]
	v_mfma_f32_16x16x32_bf16 v[72:75], v[164:167], v[232:235], v[72:75]
	s_setprio 0
	s_setprio 1
	v_mfma_f32_16x16x32_bf16 v[116:119], v[168:171], v[204:207], v[116:119]
	v_mfma_f32_16x16x32_bf16 v[112:115], v[196:199], v[204:207], v[112:115]
	v_mfma_f32_16x16x32_bf16 v[100:103], v[168:171], v[212:215], v[100:103]
	v_mfma_f32_16x16x32_bf16 v[96:99], v[196:199], v[212:215], v[96:99]
	v_mfma_f32_16x16x32_bf16 v[84:87], v[168:171], v[220:223], v[84:87]
	v_mfma_f32_16x16x32_bf16 v[80:83], v[196:199], v[220:223], v[80:83]
	v_mfma_f32_16x16x32_bf16 v[68:71], v[168:171], v[228:231], v[68:71]
	v_mfma_f32_16x16x32_bf16 v[64:67], v[196:199], v[228:231], v[64:67]
	v_mfma_f32_16x16x32_bf16 v[116:119], v[192:195], v[208:211], v[116:119]
	v_mfma_f32_16x16x32_bf16 v[112:115], v[200:203], v[208:211], v[112:115]
	v_mfma_f32_16x16x32_bf16 v[100:103], v[192:195], v[216:219], v[100:103]
	v_mfma_f32_16x16x32_bf16 v[96:99], v[200:203], v[216:219], v[96:99]
	v_mfma_f32_16x16x32_bf16 v[84:87], v[192:195], v[224:227], v[84:87]
	v_mfma_f32_16x16x32_bf16 v[80:83], v[200:203], v[224:227], v[80:83]
	v_mfma_f32_16x16x32_bf16 v[68:71], v[192:195], v[232:235], v[68:71]
	v_mfma_f32_16x16x32_bf16 v[64:67], v[200:203], v[232:235], v[64:67]
	s_setprio 0
	s_barrier
; #define PG8_STAGE(bufoff, gbase, voff) do { _Pragma("unroll") for (int _i = 0; _i < 2; ++_i) \
;         __builtin_amdgcn_global_load_lds((const unsigned*)((const char*)(gbase) + (voff)[_i]), (PG8_LAS unsigned*)(lds + (bufoff) + ldsw + _i * 8192), 16, 0, 0); } while (0)
; #define PG8_LDA(dst, b, h) do { _Pragma("unroll") for (int m = 0; m < 4; ++m) _Pragma("unroll") for (int k = 0; k < 2; ++k) dst[m][k] = *(const PG8_LAS bf16x8*)(lds + PG8_SA(b, h) + aoff + m * 2048 + k * 1024); } while (0)
; #define PG8_LDB(dst, b, h) do { _Pragma("unroll") for (int n = 0; n < 2; ++n) _Pragma("unroll") for (int k = 0; k < 2; ++k) dst[n][k] = *(const PG8_LAS bf16x8*)(lds + PG8_SB(b, h) + boff + n * 2048 + k * 1024); } while (0)
; #define PG8_MMA(ai, bj, At, Bt) do { __builtin_amdgcn_s_setprio(1); _Pragma("unroll") for (int m = 0; m < 4; ++m) _Pragma("unroll") for (int n = 0; n < 2; ++n) _Pragma("unroll") for (int k = 0; k < 2; ++k) \
;         acc[ai][bj][m][n] = __builtin_amdgcn_mfma_f32_16x16x32_bf16(Bt[n][k], At[m][k], acc[ai][bj][m][n], 0, 0, 0); __builtin_amdgcn_s_setprio(0); } while (0)
; #define PG8_WAIT_V(n) asm volatile("s_waitcnt vmcnt(" #n ")" ::: "memory")
; #define PG8_WAIT_L(n) asm volatile("s_waitcnt lgkmcnt(" #n ")" ::: "memory")
; #define PG8_BAR __builtin_amdgcn_s_barrier()
; template <class Epi, class Sched, bool ALIGN_EPI = false, bool SP2 = false>
; __device__ __forceinline__ void gemm_phase(PG8_LAS unsigned char* lds, const Gemm g, const Sched& S, const Epi& E) {
;     ...
;         for (int t = 0; t < nt; t += 2) {
;             const bool last = (t == nt - 2);
;             const char* a1 = cA + (size_t)(t + 1) * kstep;
;             const char* a2 = last ? nA : cA + (size_t)(t + 2) * kstep; const char* b2 = last ? nB : cB + (size_t)(t + 2) * kstep;
;             const char* a3 = a2 + kstep; const char* b3 = b2 + kstep;
;     ...
;             PG8_LDB(B0, 1, 0); PG8_LDB(B1, 1, 1); PG8_SCHED; PG8_LDA(At, 1, 0); PG8_STAGE(PG8_SA(0, 1), a2 + hstep, voffA);
;             PG8_WAIT_V(8); PG8_WAIT_L(0); PG8_BAR; PG8_MMA(0, 0, At, B0); PG8_MMA(0, 1, At, B1); PG8_BAR; PG8_SCHED;
;             PG8_LDA(At, 1, 1); PG8_STAGE(PG8_SB(1, 0), b3, voffB); PG8_STAGE(PG8_SB(1, 1), b3 + hstep, voffB); PG8_STAGE(PG8_SA(1, 0), a3, voffA);
;             PG8_WAIT_V(8); PG8_WAIT_L(0); PG8_BAR; PG8_MMA(1, 0, At, B0); PG8_MMA(1, 1, At, B1); PG8_BAR; PG8_SCHED;
	s_add_i32 s24, s47, s66
	v_lshl_add_u64 v[150:151], v[150:151], 0, s[14:15]
	s_mov_b32 m0, s24
	ds_read_b128 v[204:207], v155 offset:49152
	ds_read_b128 v[208:211], v155 offset:50176
	ds_read_b128 v[212:215], v155 offset:51200
	ds_read_b128 v[216:219], v155 offset:52224
	ds_read_b128 v[220:223], v155 offset:53248
	ds_read_b128 v[224:227], v155 offset:54272
	ds_read_b128 v[228:231], v155 offset:55296
	ds_read_b128 v[232:235], v155 offset:56320
	global_load_lds_dwordx4 v[150:151], off
	s_add_i32 m0, s24, 0x2000
	s_add_u32 s24, s62, 0x40080
	v_lshl_add_u64 v[150:151], v[236:237], 0, s[14:15]
	s_addc_u32 s25, s63, 0
	s_add_i32 s47, s50, s66
	global_load_lds_dwordx4 v[150:151], off
	v_lshl_add_u64 v[150:151], s[24:25], 0, v[132:133]
	s_mov_b32 m0, s47
	s_nop 0
	global_load_lds_dwordx4 v[150:151], off
	v_lshl_add_u64 v[150:151], s[24:25], 0, v[128:129]
	s_add_i32 m0, s47, 0x2000
	s_nop 0
	global_load_lds_dwordx4 v[150:151], off
	v_lshl_add_u64 v[150:151], v[238:239], 0, s[14:15]
	s_mov_b32 m0, s88
	s_nop 0
	global_load_lds_dwordx4 v[150:151], off
	v_lshl_add_u64 v[150:151], v[240:241], 0, s[14:15]
	s_mov_b32 m0, s89
	s_nop 0
	global_load_lds_dwordx4 v[150:151], off
	s_waitcnt vmcnt(8)
	s_waitcnt lgkmcnt(0)
	s_barrier
	s_setprio 1
	s_waitcnt lgkmcnt(0)
	v_mfma_f32_16x16x32_bf16 v[60:63], v[146:149], v[204:207], v[60:63]
	v_mfma_f32_16x16x32_bf16 v[56:59], v[160:163], v[204:207], v[56:59]
	v_mfma_f32_16x16x32_bf16 v[44:47], v[146:149], v[212:215], v[44:47]
	v_mfma_f32_16x16x32_bf16 v[40:43], v[160:163], v[212:215], v[40:43]
	v_mfma_f32_16x16x32_bf16 v[28:31], v[146:149], v[220:223], v[28:31]
	v_mfma_f32_16x16x32_bf16 v[24:27], v[160:163], v[220:223], v[24:27]
	v_mfma_f32_16x16x32_bf16 v[12:15], v[146:149], v[228:231], v[12:15]
	v_mfma_f32_16x16x32_bf16 v[8:11], v[160:163], v[228:231], v[8:11]
	v_mfma_f32_16x16x32_bf16 v[60:63], v[156:159], v[208:211], v[60:63]
	v_mfma_f32_16x16x32_bf16 v[56:59], v[164:167], v[208:211], v[56:59]
	v_mfma_f32_16x16x32_bf16 v[44:47], v[156:159], v[216:219], v[44:47]
	v_mfma_f32_16x16x32_bf16 v[40:43], v[164:167], v[216:219], v[40:43]
	v_mfma_f32_16x16x32_bf16 v[28:31], v[156:159], v[224:227], v[28:31]
	v_mfma_f32_16x16x32_bf16 v[24:27], v[164:167], v[224:227], v[24:27]
	v_mfma_f32_16x16x32_bf16 v[12:15], v[156:159], v[232:235], v[12:15]
	v_mfma_f32_16x16x32_bf16 v[8:11], v[164:167], v[232:235], v[8:11]
	s_setprio 0
	s_setprio 1
	v_mfma_f32_16x16x32_bf16 v[52:55], v[168:171], v[204:207], v[52:55]
	v_mfma_f32_16x16x32_bf16 v[48:51], v[196:199], v[204:207], v[48:51]
	v_mfma_f32_16x16x32_bf16 v[36:39], v[168:171], v[212:215], v[36:39]
	v_mfma_f32_16x16x32_bf16 v[32:35], v[196:199], v[212:215], v[32:35]
	v_mfma_f32_16x16x32_bf16 v[20:23], v[168:171], v[220:223], v[20:23]
	v_mfma_f32_16x16x32_bf16 v[16:19], v[196:199], v[220:223], v[16:19]
	v_mfma_f32_16x16x32_bf16 v[4:7], v[168:171], v[228:231], v[4:7]
	v_mfma_f32_16x16x32_bf16 v[0:3], v[196:199], v[228:231], v[0:3]
	v_mfma_f32_16x16x32_bf16 v[52:55], v[192:195], v[208:211], v[52:55]
	v_mfma_f32_16x16x32_bf16 v[48:51], v[200:203], v[208:211], v[48:51]
	v_mfma_f32_16x16x32_bf16 v[36:39], v[192:195], v[216:219], v[36:39]
	v_mfma_f32_16x16x32_bf16 v[32:35], v[200:203], v[216:219], v[32:35]
	v_mfma_f32_16x16x32_bf16 v[20:23], v[192:195], v[224:227], v[20:23]
	v_mfma_f32_16x16x32_bf16 v[16:19], v[200:203], v[224:227], v[16:19]
	v_mfma_f32_16x16x32_bf16 v[4:7], v[192:195], v[232:235], v[4:7]
	v_mfma_f32_16x16x32_bf16 v[0:3], v[200:203], v[232:235], v[0:3]
	s_setprio 0
	s_barrier
	s_add_i32 s45, s45, 2
	s_add_u32 s60, s60, 0x100
	s_addc_u32 s61, s61, 0
	s_add_u32 s33, s33, 0x100
	s_addc_u32 s44, s44, 0
	s_cmp_gt_u32 s45, 13

; #define PG8_STAGE(bufoff, gbase, voff) do { _Pragma("unroll") for (int _i = 0; _i < 2; ++_i) \
;         __builtin_amdgcn_global_load_lds((const unsigned*)((const char*)(gbase) + (voff)[_i]), (PG8_LAS unsigned*)(lds + (bufoff) + ldsw + _i * 8192), 16, 0, 0); } while (0)
; #define PG8_LDA(dst, b, h) do { _Pragma("unroll") for (int m = 0; m < 4; ++m) _Pragma("unroll") for (int k = 0; k < 2; ++k) dst[m][k] = *(const PG8_LAS bf16x8*)(lds + PG8_SA(b, h) + aoff + m * 2048 + k * 1024); } while (0)
; #define PG8_LDB(dst, b, h) do { _Pragma("unroll") for (int n = 0; n < 2; ++n) _Pragma("unroll") for (int k = 0; k < 2; ++k) dst[n][k] = *(const PG8_LAS bf16x8*)(lds + PG8_SB(b, h) + boff + n * 2048 + k * 1024); } while (0)
; template <class Epi, class Sched, bool ALIGN_EPI = false, bool SP2 = false>
; __device__ __forceinline__ void gemm_phase(PG8_LAS unsigned char* lds, const Gemm g, const Sched& S, const Epi& E) {
;     ...
;         const bool has_next = S.next(ui + 1, nxt);
;         const char* nA = has_next ? (const char*)g.A + (size_t)nxt.pm * tstep : cA; const char* nB = has_next ? (const char*)g.Bt + (size_t)nxt.pn * tstep : cB;
;         for (int t = 0; t < nt; t += 2) {
;             const bool last = (t == nt - 2);
;             const char* a1 = cA + (size_t)(t + 1) * kstep;
;             const char* a2 = last ? nA : cA + (size_t)(t + 2) * kstep; const char* b2 = last ? nB : cB + (size_t)(t + 2) * kstep;
;             const char* a3 = a2 + kstep; const char* b3 = b2 + kstep;
;             if (last && has_next) S.a_ready(nxt);
;             if constexpr (SP2) {
;             PG8_LDB(B0, 0, 0); PG8_LDB(B1, 0, 1); PG8_SCHED; PG8_LDA(At, 0, 0); PG8_STAGE(PG8_SA(1, 1), a1 + hstep, voffA);
;             PG8_WAIT_V(8); PG8_WAIT_L(0); PG8_BAR; PG8_MMA(0, 0, At, B0); PG8_MMA(0, 1, At, B1); PG8_BAR; PG8_SCHED;
;             PG8_LDA(At, 0, 1); PG8_STAGE(PG8_SB(0, 0), b2, voffB); PG8_STAGE(PG8_SB(0, 1), b2 + hstep, voffB); PG8_STAGE(PG8_SA(0, 0), a2, voffA);
;             PG8_WAIT_V(8); PG8_WAIT_L(0); PG8_BAR; PG8_MMA(1, 0, At, B0); PG8_MMA(1, 1, At, B1); PG8_BAR; PG8_SCHED;
;     ...
;         for (int a = 0; a < 2; ++a)
; #pragma unroll
;             for (int b = 0; b < 2; ++b)
; #pragma unroll
;                 for (int m = 0; m < 4; ++m)
; #pragma unroll
;                     for (int n = 0; n < 2; ++n) acc[a][b][m][n] = (f32x4){0.f, 0.f, 0.f, 0.f};
.LBB0_121:
	s_add_u32 s22, s46, 0x100
	s_addc_u32 s33, s47, 0
	s_mov_b32 s50, -2
	s_add_u32 s42, s44, 0x100
	s_addc_u32 s43, s45, 0
	s_add_i32 s24, 0, 0x10000
	s_cmp_eq_u32 s50, 8
	s_cselect_b32 s69, s65, s43
	s_cselect_b32 s68, s64, s42
	s_cselect_b32 s47, s67, s33
	s_cselect_b32 s46, s66, s22
	s_add_i32 s51, 0, 0x14000
	v_add_u32_e32 v162, s24, v150
	v_add_u32_e32 v170, s51, v150
	ds_read_b128 v[146:149], v162
	ds_read_b128 v[154:157], v162 offset:1024
	ds_read_b128 v[158:161], v162 offset:2048
	ds_read_b128 v[162:165], v162 offset:3072
	ds_read_b128 v[166:169], v170
	ds_read_b128 v[192:195], v170 offset:1024
	ds_read_b128 v[196:199], v170 offset:2048
	ds_read_b128 v[200:203], v170 offset:3072
	v_lshl_add_u64 v[170:171], s[44:45], 0, v[142:143]
	s_add_i32 m0, s71, 0xc000
	ds_read_b128 v[204:207], v153
	ds_read_b128 v[208:211], v153 offset:1024
	ds_read_b128 v[212:215], v153 offset:2048
	ds_read_b128 v[216:219], v153 offset:3072
	ds_read_b128 v[220:223], v153 offset:4096
	ds_read_b128 v[224:227], v153 offset:5120
	ds_read_b128 v[228:231], v153 offset:6144
	ds_read_b128 v[232:235], v153 offset:7168
	global_load_lds_dwordx4 v[170:171], off
	v_lshl_add_u64 v[170:171], s[44:45], 0, v[144:145]
	s_add_i32 m0, s71, 0xe000
	s_nop 0
	global_load_lds_dwordx4 v[170:171], off
	s_waitcnt vmcnt(8)
	s_waitcnt lgkmcnt(0)
	s_barrier
	s_setprio 1
	s_waitcnt lgkmcnt(0)
	v_mfma_f32_16x16x32_bf16 v[124:127], v[146:149], v[204:207], 0
	v_mfma_f32_16x16x32_bf16 v[120:123], v[158:161], v[204:207], 0
	v_mfma_f32_16x16x32_bf16 v[108:111], v[146:149], v[212:215], 0
	v_mfma_f32_16x16x32_bf16 v[104:107], v[158:161], v[212:215], 0
	v_mfma_f32_16x16x32_bf16 v[92:95], v[146:149], v[220:223], 0
	v_mfma_f32_16x16x32_bf16 v[88:91], v[158:161], v[220:223], 0
	v_mfma_f32_16x16x32_bf16 v[76:79], v[146:149], v[228:231], 0
	v_mfma_f32_16x16x32_bf16 v[72:75], v[158:161], v[228:231], 0
	v_mfma_f32_16x16x32_bf16 v[124:127], v[154:157], v[208:211], v[124:127]
	v_mfma_f32_16x16x32_bf16 v[120:123], v[162:165], v[208:211], v[120:123]
	v_mfma_f32_16x16x32_bf16 v[108:111], v[154:157], v[216:219], v[108:111]
	v_mfma_f32_16x16x32_bf16 v[104:107], v[162:165], v[216:219], v[104:107]
	v_mfma_f32_16x16x32_bf16 v[92:95], v[154:157], v[224:227], v[92:95]
	v_mfma_f32_16x16x32_bf16 v[88:91], v[162:165], v[224:227], v[88:91]
	v_mfma_f32_16x16x32_bf16 v[76:79], v[154:157], v[232:235], v[76:79]
	v_mfma_f32_16x16x32_bf16 v[72:75], v[162:165], v[232:235], v[72:75]
	s_setprio 0
	s_setprio 1
	v_mfma_f32_16x16x32_bf16 v[116:119], v[166:169], v[204:207], 0
	v_mfma_f32_16x16x32_bf16 v[112:115], v[196:199], v[204:207], 0
	v_mfma_f32_16x16x32_bf16 v[100:103], v[166:169], v[212:215], 0
	v_mfma_f32_16x16x32_bf16 v[96:99], v[196:199], v[212:215], 0
	v_mfma_f32_16x16x32_bf16 v[84:87], v[166:169], v[220:223], 0
	v_mfma_f32_16x16x32_bf16 v[80:83], v[196:199], v[220:223], 0
	v_mfma_f32_16x16x32_bf16 v[68:71], v[166:169], v[228:231], 0
	v_mfma_f32_16x16x32_bf16 v[64:67], v[196:199], v[228:231], 0
	v_mfma_f32_16x16x32_bf16 v[116:119], v[192:195], v[208:211], v[116:119]
	v_mfma_f32_16x16x32_bf16 v[112:115], v[200:203], v[208:211], v[112:115]
	v_mfma_f32_16x16x32_bf16 v[100:103], v[192:195], v[216:219], v[100:103]
	v_mfma_f32_16x16x32_bf16 v[96:99], v[200:203], v[216:219], v[96:99]
	v_mfma_f32_16x16x32_bf16 v[84:87], v[192:195], v[224:227], v[84:87]
	v_mfma_f32_16x16x32_bf16 v[80:83], v[200:203], v[224:227], v[80:83]
	v_mfma_f32_16x16x32_bf16 v[68:71], v[192:195], v[232:235], v[68:71]
	v_mfma_f32_16x16x32_bf16 v[64:67], v[200:203], v[232:235], v[64:67]
	s_setprio 0
	s_barrier
	s_add_i32 s24, s24, s29
	v_lshl_add_u64 v[170:171], s[46:47], 0, v[128:129]
	s_mov_b32 m0, s24
	ds_read_b128 v[204:207], v153 offset:16384
	ds_read_b128 v[208:211], v153 offset:17408
	ds_read_b128 v[212:215], v153 offset:18432
	ds_read_b128 v[216:219], v153 offset:19456
	ds_read_b128 v[220:223], v153 offset:20480
	ds_read_b128 v[224:227], v153 offset:21504
	ds_read_b128 v[228:231], v153 offset:22528
	ds_read_b128 v[232:235], v153 offset:23552
	global_load_lds_dwordx4 v[170:171], off
	s_add_i32 m0, s24, 0x2000
	s_add_u32 s24, s46, 0x30000
	v_lshl_add_u64 v[236:237], s[46:47], 0, v[130:131]
	s_addc_u32 s25, s47, 0
	s_add_i32 s44, s51, s29
	global_load_lds_dwordx4 v[236:237], off
	v_lshl_add_u64 v[238:239], s[24:25], 0, v[128:129]
	s_mov_b32 m0, s44
	v_lshl_add_u64 v[240:241], s[68:69], 0, v[130:131]
	global_load_lds_dwordx4 v[238:239], off
	v_lshl_add_u64 v[238:239], s[24:25], 0, v[130:131]
	s_add_i32 m0, s44, 0x2000
	s_nop 0
	global_load_lds_dwordx4 v[238:239], off
	v_lshl_add_u64 v[238:239], s[68:69], 0, v[128:129]
	s_mov_b32 m0, s71
	s_nop 0
	global_load_lds_dwordx4 v[238:239], off
	s_mov_b32 m0, s87
	s_nop 0
	global_load_lds_dwordx4 v[240:241], off
	s_waitcnt vmcnt(8)
	s_waitcnt lgkmcnt(0)
	s_barrier
; #define PG8_STAGE(bufoff, gbase, voff) do { _Pragma("unroll") for (int _i = 0; _i < 2; ++_i) \
;         __builtin_amdgcn_global_load_lds((const unsigned*)((const char*)(gbase) + (voff)[_i]), (PG8_LAS unsigned*)(lds + (bufoff) + ldsw + _i * 8192), 16, 0, 0); } while (0)
; #define PG8_LDA(dst, b, h) do { _Pragma("unroll") for (int m = 0; m < 4; ++m) _Pragma("unroll") for (int k = 0; k < 2; ++k) dst[m][k] = *(const PG8_LAS bf16x8*)(lds + PG8_SA(b, h) + aoff + m * 2048 + k * 1024); } while (0)
; #define PG8_LDB(dst, b, h) do { _Pragma("unroll") for (int n = 0; n < 2; ++n) _Pragma("unroll") for (int k = 0; k < 2; ++k) dst[n][k] = *(const PG8_LAS bf16x8*)(lds + PG8_SB(b, h) + boff + n * 2048 + k * 1024); } while (0)
; #define PG8_MMA(ai, bj, At, Bt) do { __builtin_amdgcn_s_setprio(1); _Pragma("unroll") for (int m = 0; m < 4; ++m) _Pragma("unroll") for (int n = 0; n < 2; ++n) _Pragma("unroll") for (int k = 0; k < 2; ++k) \
;         acc[ai][bj][m][n] = __builtin_amdgcn_mfma_f32_16x16x32_bf16(Bt[n][k], At[m][k], acc[ai][bj][m][n], 0, 0, 0); __builtin_amdgcn_s_setprio(0); } while (0)
; #define PG8_WAIT_V(n) asm volatile("s_waitcnt vmcnt(" #n ")" ::: "memory")
; #define PG8_WAIT_L(n) asm volatile("s_waitcnt lgkmcnt(" #n ")" ::: "memory")
; #define PG8_BAR __builtin_amdgcn_s_barrier()
; #define PG8_SCHED __builtin_amdgcn_sched_barrier(0)
; template <class Epi, class Sched, bool ALIGN_EPI = false, bool SP2 = false>
; __device__ __forceinline__ void gemm_phase(PG8_LAS unsigned char* lds, const Gemm g, const Sched& S, const Epi& E) {
;     ...
;             PG8_WAIT_V(8); PG8_WAIT_L(0); PG8_BAR; PG8_MMA(1, 0, At, B0); PG8_MMA(1, 1, At, B1); PG8_BAR; PG8_SCHED;
;             PG8_LDB(B0, 1, 0); PG8_LDB(B1, 1, 1); PG8_SCHED; PG8_LDA(At, 1, 0); PG8_STAGE(PG8_SA(0, 1), a2 + hstep, voffA);
;             PG8_WAIT_V(8); PG8_WAIT_L(0); PG8_BAR; PG8_MMA(0, 0, At, B0); PG8_MMA(0, 1, At, B1); PG8_BAR; PG8_SCHED;
;             PG8_LDA(At, 1, 1); PG8_STAGE(PG8_SB(1, 0), b3, voffB); PG8_STAGE(PG8_SB(1, 1), b3 + hstep, voffB); PG8_STAGE(PG8_SA(1, 0), a3, voffA);
;             PG8_WAIT_V(8); PG8_WAIT_L(0); PG8_BAR; PG8_MMA(1, 0, At, B0); PG8_MMA(1, 1, At, B1); PG8_BAR; PG8_SCHED;
	s_setprio 1
	s_waitcnt lgkmcnt(0)
	v_mfma_f32_16x16x32_bf16 v[60:63], v[146:149], v[204:207], 0
	v_mfma_f32_16x16x32_bf16 v[56:59], v[158:161], v[204:207], 0
	v_mfma_f32_16x16x32_bf16 v[44:47], v[146:149], v[212:215], 0
	v_mfma_f32_16x16x32_bf16 v[40:43], v[158:161], v[212:215], 0
	v_mfma_f32_16x16x32_bf16 v[28:31], v[146:149], v[220:223], 0
	v_mfma_f32_16x16x32_bf16 v[24:27], v[158:161], v[220:223], 0
	v_mfma_f32_16x16x32_bf16 v[12:15], v[146:149], v[228:231], 0
	v_mfma_f32_16x16x32_bf16 v[8:11], v[158:161], v[228:231], 0
	v_mfma_f32_16x16x32_bf16 v[60:63], v[154:157], v[208:211], v[60:63]
	v_mfma_f32_16x16x32_bf16 v[56:59], v[162:165], v[208:211], v[56:59]
	v_mfma_f32_16x16x32_bf16 v[44:47], v[154:157], v[216:219], v[44:47]
	v_mfma_f32_16x16x32_bf16 v[40:43], v[162:165], v[216:219], v[40:43]
	v_mfma_f32_16x16x32_bf16 v[28:31], v[154:157], v[224:227], v[28:31]
	v_mfma_f32_16x16x32_bf16 v[24:27], v[162:165], v[224:227], v[24:27]
	v_mfma_f32_16x16x32_bf16 v[12:15], v[154:157], v[232:235], v[12:15]
	v_mfma_f32_16x16x32_bf16 v[8:11], v[162:165], v[232:235], v[8:11]
	s_setprio 0
	s_setprio 1
	v_mfma_f32_16x16x32_bf16 v[52:55], v[166:169], v[204:207], 0
	v_mfma_f32_16x16x32_bf16 v[48:51], v[196:199], v[204:207], 0
	v_mfma_f32_16x16x32_bf16 v[36:39], v[166:169], v[212:215], 0
	v_mfma_f32_16x16x32_bf16 v[32:35], v[196:199], v[212:215], 0
	v_mfma_f32_16x16x32_bf16 v[20:23], v[166:169], v[220:223], 0
	v_mfma_f32_16x16x32_bf16 v[16:19], v[196:199], v[220:223], 0
	v_mfma_f32_16x16x32_bf16 v[4:7], v[166:169], v[228:231], 0
	v_mfma_f32_16x16x32_bf16 v[0:3], v[196:199], v[228:231], 0
	v_mfma_f32_16x16x32_bf16 v[52:55], v[192:195], v[208:211], v[52:55]
	v_mfma_f32_16x16x32_bf16 v[48:51], v[200:203], v[208:211], v[48:51]
	v_mfma_f32_16x16x32_bf16 v[36:39], v[192:195], v[216:219], v[36:39]
	v_mfma_f32_16x16x32_bf16 v[32:35], v[200:203], v[216:219], v[32:35]
	v_mfma_f32_16x16x32_bf16 v[20:23], v[192:195], v[224:227], v[20:23]
	v_mfma_f32_16x16x32_bf16 v[16:19], v[200:203], v[224:227], v[16:19]
	v_mfma_f32_16x16x32_bf16 v[4:7], v[192:195], v[232:235], v[4:7]
	v_mfma_f32_16x16x32_bf16 v[0:3], v[200:203], v[232:235], v[0:3]
	s_setprio 0
	s_barrier
	s_add_i32 s44, 0, 0x18000
	s_add_i32 s45, 0, 0x1c000
	v_add_u32_e32 v162, s44, v150
	v_add_u32_e32 v184, s45, v150
	ds_read_b128 v[146:149], v162
	ds_read_b128 v[154:157], v162 offset:1024
	ds_read_b128 v[158:161], v162 offset:2048
	ds_read_b128 v[162:165], v162 offset:3072
	ds_read_b128 v[166:169], v184
	ds_read_b128 v[192:195], v184 offset:1024
	ds_read_b128 v[196:199], v184 offset:2048
	ds_read_b128 v[200:203], v184 offset:3072
	s_add_u32 s24, s68, 0x30000
	s_addc_u32 s25, s69, 0
	s_mov_b32 m0, s88
	v_lshl_add_u64 v[242:243], s[24:25], 0, v[128:129]
	ds_read_b128 v[204:207], v153 offset:32768
	ds_read_b128 v[208:211], v153 offset:33792
	ds_read_b128 v[212:215], v153 offset:34816
	ds_read_b128 v[216:219], v153 offset:35840
	ds_read_b128 v[220:223], v153 offset:36864
	ds_read_b128 v[224:227], v153 offset:37888
	ds_read_b128 v[228:231], v153 offset:38912
	ds_read_b128 v[232:235], v153 offset:39936
	global_load_lds_dwordx4 v[242:243], off
	v_lshl_add_u64 v[242:243], s[24:25], 0, v[130:131]
	s_mov_b32 m0, s89
	s_nop 0
	global_load_lds_dwordx4 v[242:243], off
	s_waitcnt vmcnt(8)
	s_waitcnt lgkmcnt(0)
	s_barrier
	s_setprio 1
	s_waitcnt lgkmcnt(0)
	v_mfma_f32_16x16x32_bf16 v[124:127], v[146:149], v[204:207], v[124:127]
	v_mfma_f32_16x16x32_bf16 v[120:123], v[158:161], v[204:207], v[120:123]
	v_mfma_f32_16x16x32_bf16 v[108:111], v[146:149], v[212:215], v[108:111]
	v_mfma_f32_16x16x32_bf16 v[104:107], v[158:161], v[212:215], v[104:107]
	v_mfma_f32_16x16x32_bf16 v[92:95], v[146:149], v[220:223], v[92:95]
	v_mfma_f32_16x16x32_bf16 v[88:91], v[158:161], v[220:223], v[88:91]
	v_mfma_f32_16x16x32_bf16 v[76:79], v[146:149], v[228:231], v[76:79]
	v_mfma_f32_16x16x32_bf16 v[72:75], v[158:161], v[228:231], v[72:75]
	v_mfma_f32_16x16x32_bf16 v[124:127], v[154:157], v[208:211], v[124:127]
	v_mfma_f32_16x16x32_bf16 v[120:123], v[162:165], v[208:211], v[120:123]
	v_mfma_f32_16x16x32_bf16 v[108:111], v[154:157], v[216:219], v[108:111]
	v_mfma_f32_16x16x32_bf16 v[104:107], v[162:165], v[216:219], v[104:107]
	v_mfma_f32_16x16x32_bf16 v[92:95], v[154:157], v[224:227], v[92:95]
	v_mfma_f32_16x16x32_bf16 v[88:91], v[162:165], v[224:227], v[88:91]
	v_mfma_f32_16x16x32_bf16 v[76:79], v[154:157], v[232:235], v[76:79]
	v_mfma_f32_16x16x32_bf16 v[72:75], v[162:165], v[232:235], v[72:75]
	s_setprio 0
	s_setprio 1
	v_mfma_f32_16x16x32_bf16 v[116:119], v[166:169], v[204:207], v[116:119]
	v_mfma_f32_16x16x32_bf16 v[112:115], v[196:199], v[204:207], v[112:115]
	v_mfma_f32_16x16x32_bf16 v[100:103], v[166:169], v[212:215], v[100:103]
	v_mfma_f32_16x16x32_bf16 v[96:99], v[196:199], v[212:215], v[96:99]
	v_mfma_f32_16x16x32_bf16 v[84:87], v[166:169], v[220:223], v[84:87]
	v_mfma_f32_16x16x32_bf16 v[80:83], v[196:199], v[220:223], v[80:83]
	v_mfma_f32_16x16x32_bf16 v[68:71], v[166:169], v[228:231], v[68:71]
	v_mfma_f32_16x16x32_bf16 v[64:67], v[196:199], v[228:231], v[64:67]
	v_mfma_f32_16x16x32_bf16 v[116:119], v[192:195], v[208:211], v[116:119]
	v_mfma_f32_16x16x32_bf16 v[112:115], v[200:203], v[208:211], v[112:115]
	v_mfma_f32_16x16x32_bf16 v[100:103], v[192:195], v[216:219], v[100:103]
	v_mfma_f32_16x16x32_bf16 v[96:99], v[200:203], v[216:219], v[96:99]
	v_mfma_f32_16x16x32_bf16 v[84:87], v[192:195], v[224:227], v[84:87]
	v_mfma_f32_16x16x32_bf16 v[80:83], v[200:203], v[224:227], v[80:83]
	v_mfma_f32_16x16x32_bf16 v[68:71], v[192:195], v[232:235], v[68:71]
	v_mfma_f32_16x16x32_bf16 v[64:67], v[200:203], v[232:235], v[64:67]
	s_setprio 0
	s_barrier
; #define PG8_STAGE(bufoff, gbase, voff) do { _Pragma("unroll") for (int _i = 0; _i < 2; ++_i) \
;         __builtin_amdgcn_global_load_lds((const unsigned*)((const char*)(gbase) + (voff)[_i]), (PG8_LAS unsigned*)(lds + (bufoff) + ldsw + _i * 8192), 16, 0, 0); } while (0)
; #define PG8_LDA(dst, b, h) do { _Pragma("unroll") for (int m = 0; m < 4; ++m) _Pragma("unroll") for (int k = 0; k < 2; ++k) dst[m][k] = *(const PG8_LAS bf16x8*)(lds + PG8_SA(b, h) + aoff + m * 2048 + k * 1024); } while (0)
; #define PG8_LDB(dst, b, h) do { _Pragma("unroll") for (int n = 0; n < 2; ++n) _Pragma("unroll") for (int k = 0; k < 2; ++k) dst[n][k] = *(const PG8_LAS bf16x8*)(lds + PG8_SB(b, h) + boff + n * 2048 + k * 1024); } while (0)
; #define PG8_MMA(ai, bj, At, Bt) do { __builtin_amdgcn_s_setprio(1); _Pragma("unroll") for (int m = 0; m < 4; ++m) _Pragma("unroll") for (int n = 0; n < 2; ++n) _Pragma("unroll") for (int k = 0; k < 2; ++k) \
;         acc[ai][bj][m][n] = __builtin_amdgcn_mfma_f32_16x16x32_bf16(Bt[n][k], At[m][k], acc[ai][bj][m][n], 0, 0, 0); __builtin_amdgcn_s_setprio(0); } while (0)
; #define PG8_WAIT_V(n) asm volatile("s_waitcnt vmcnt(" #n ")" ::: "memory")
; #define PG8_WAIT_L(n) asm volatile("s_waitcnt lgkmcnt(" #n ")" ::: "memory")
; #define PG8_BAR __builtin_amdgcn_s_barrier()
; template <class Epi, class Sched, bool ALIGN_EPI = false, bool SP2 = false>
; __device__ __forceinline__ void gemm_phase(PG8_LAS unsigned char* lds, const Gemm g, const Sched& S, const Epi& E) {
;     ...
;         for (int t = 0; t < nt; t += 2) {
;             const bool last = (t == nt - 2);
;             const char* a1 = cA + (size_t)(t + 1) * kstep;
;             const char* a2 = last ? nA : cA + (size_t)(t + 2) * kstep; const char* b2 = last ? nB : cB + (size_t)(t + 2) * kstep;
;             const char* a3 = a2 + kstep; const char* b3 = b2 + kstep;
;     ...
;             PG8_LDB(B0, 1, 0); PG8_LDB(B1, 1, 1); PG8_SCHED; PG8_LDA(At, 1, 0); PG8_STAGE(PG8_SA(0, 1), a2 + hstep, voffA);
;             PG8_WAIT_V(8); PG8_WAIT_L(0); PG8_BAR; PG8_MMA(0, 0, At, B0); PG8_MMA(0, 1, At, B1); PG8_BAR; PG8_SCHED;
;             PG8_LDA(At, 1, 1); PG8_STAGE(PG8_SB(1, 0), b3, voffB); PG8_STAGE(PG8_SB(1, 1), b3 + hstep, voffB); PG8_STAGE(PG8_SA(1, 0), a3, voffA);
;             PG8_WAIT_V(8); PG8_WAIT_L(0); PG8_BAR; PG8_MMA(1, 0, At, B0); PG8_MMA(1, 1, At, B1); PG8_BAR; PG8_SCHED;
	s_add_i32 s24, s44, s29
	v_lshl_add_u64 v[170:171], v[170:171], 0, s[14:15]
	s_mov_b32 m0, s24
	ds_read_b128 v[204:207], v153 offset:49152
	ds_read_b128 v[208:211], v153 offset:50176
	ds_read_b128 v[212:215], v153 offset:51200
	ds_read_b128 v[216:219], v153 offset:52224
	ds_read_b128 v[220:223], v153 offset:53248
	ds_read_b128 v[224:227], v153 offset:54272
	ds_read_b128 v[228:231], v153 offset:55296
	ds_read_b128 v[232:235], v153 offset:56320
	global_load_lds_dwordx4 v[170:171], off
	s_add_i32 m0, s24, 0x2000
	s_add_u32 s24, s46, 0x30080
	v_lshl_add_u64 v[170:171], v[236:237], 0, s[14:15]
	s_addc_u32 s25, s47, 0
	s_add_i32 s44, s45, s29
	global_load_lds_dwordx4 v[170:171], off
	v_lshl_add_u64 v[170:171], s[24:25], 0, v[128:129]
	s_mov_b32 m0, s44
	s_nop 0
	global_load_lds_dwordx4 v[170:171], off
	v_lshl_add_u64 v[170:171], s[24:25], 0, v[130:131]
	s_add_i32 m0, s44, 0x2000
	s_nop 0
	global_load_lds_dwordx4 v[170:171], off
	v_lshl_add_u64 v[170:171], v[238:239], 0, s[14:15]
	s_mov_b32 m0, s91
	s_nop 0
	global_load_lds_dwordx4 v[170:171], off
	v_lshl_add_u64 v[170:171], v[240:241], 0, s[14:15]
	s_mov_b32 m0, s92
	s_nop 0
	global_load_lds_dwordx4 v[170:171], off
	s_waitcnt vmcnt(8)
	s_waitcnt lgkmcnt(0)
	s_barrier
	s_setprio 1
	s_waitcnt lgkmcnt(0)
	v_mfma_f32_16x16x32_bf16 v[60:63], v[146:149], v[204:207], v[60:63]
	v_mfma_f32_16x16x32_bf16 v[56:59], v[158:161], v[204:207], v[56:59]
	v_mfma_f32_16x16x32_bf16 v[44:47], v[146:149], v[212:215], v[44:47]
	v_mfma_f32_16x16x32_bf16 v[40:43], v[158:161], v[212:215], v[40:43]
	v_mfma_f32_16x16x32_bf16 v[28:31], v[146:149], v[220:223], v[28:31]
	v_mfma_f32_16x16x32_bf16 v[24:27], v[158:161], v[220:223], v[24:27]
	v_mfma_f32_16x16x32_bf16 v[12:15], v[146:149], v[228:231], v[12:15]
	v_mfma_f32_16x16x32_bf16 v[8:11], v[158:161], v[228:231], v[8:11]
	v_mfma_f32_16x16x32_bf16 v[60:63], v[154:157], v[208:211], v[60:63]
	v_mfma_f32_16x16x32_bf16 v[56:59], v[162:165], v[208:211], v[56:59]
	v_mfma_f32_16x16x32_bf16 v[44:47], v[154:157], v[216:219], v[44:47]
	v_mfma_f32_16x16x32_bf16 v[40:43], v[162:165], v[216:219], v[40:43]
	v_mfma_f32_16x16x32_bf16 v[28:31], v[154:157], v[224:227], v[28:31]
	v_mfma_f32_16x16x32_bf16 v[24:27], v[162:165], v[224:227], v[24:27]
	v_mfma_f32_16x16x32_bf16 v[12:15], v[154:157], v[232:235], v[12:15]
	v_mfma_f32_16x16x32_bf16 v[8:11], v[162:165], v[232:235], v[8:11]
	s_setprio 0
	s_setprio 1
	v_mfma_f32_16x16x32_bf16 v[52:55], v[166:169], v[204:207], v[52:55]
	v_mfma_f32_16x16x32_bf16 v[48:51], v[196:199], v[204:207], v[48:51]
	v_mfma_f32_16x16x32_bf16 v[36:39], v[166:169], v[212:215], v[36:39]
	v_mfma_f32_16x16x32_bf16 v[32:35], v[196:199], v[212:215], v[32:35]
	v_mfma_f32_16x16x32_bf16 v[20:23], v[166:169], v[220:223], v[20:23]
	v_mfma_f32_16x16x32_bf16 v[16:19], v[196:199], v[220:223], v[16:19]
	v_mfma_f32_16x16x32_bf16 v[4:7], v[166:169], v[228:231], v[4:7]
	v_mfma_f32_16x16x32_bf16 v[0:3], v[196:199], v[228:231], v[0:3]
	v_mfma_f32_16x16x32_bf16 v[52:55], v[192:195], v[208:211], v[52:55]
	v_mfma_f32_16x16x32_bf16 v[48:51], v[200:203], v[208:211], v[48:51]
	v_mfma_f32_16x16x32_bf16 v[36:39], v[192:195], v[216:219], v[36:39]
	v_mfma_f32_16x16x32_bf16 v[32:35], v[200:203], v[216:219], v[32:35]
	v_mfma_f32_16x16x32_bf16 v[20:23], v[192:195], v[224:227], v[20:23]
	v_mfma_f32_16x16x32_bf16 v[16:19], v[200:203], v[224:227], v[16:19]
	v_mfma_f32_16x16x32_bf16 v[4:7], v[192:195], v[232:235], v[4:7]
	v_mfma_f32_16x16x32_bf16 v[0:3], v[200:203], v[232:235], v[0:3]
	s_setprio 0
	s_barrier
	s_add_i32 s50, s50, 2
	s_add_u32 s22, s22, 0x100
	s_addc_u32 s33, s33, 0
	s_cmp_gt_u32 s50, 9
	s_mov_b64 s[44:45], s[42:43]

; #define PG8_STAGE(bufoff, gbase, voff) do { _Pragma("unroll") for (int _i = 0; _i < 2; ++_i) \
;         __builtin_amdgcn_global_load_lds((const unsigned*)((const char*)(gbase) + (voff)[_i]), (PG8_LAS unsigned*)(lds + (bufoff) + ldsw + _i * 8192), 16, 0, 0); } while (0)
; #define PG8_LDA(dst, b, h) do { _Pragma("unroll") for (int m = 0; m < 4; ++m) _Pragma("unroll") for (int k = 0; k < 2; ++k) dst[m][k] = *(const PG8_LAS bf16x8*)(lds + PG8_SA(b, h) + aoff + m * 2048 + k * 1024); } while (0)
; #define PG8_LDB(dst, b, h) do { _Pragma("unroll") for (int n = 0; n < 2; ++n) _Pragma("unroll") for (int k = 0; k < 2; ++k) dst[n][k] = *(const PG8_LAS bf16x8*)(lds + PG8_SB(b, h) + boff + n * 2048 + k * 1024); } while (0)
; template <class Epi, class Sched, bool ALIGN_EPI = false, bool SP2 = false>
; __device__ __forceinline__ void gemm_phase(PG8_LAS unsigned char* lds, const Gemm g, const Sched& S, const Epi& E) {
;     ...
;         const bool has_next = S.next(ui + 1, nxt);
;         const char* nA = has_next ? (const char*)g.A + (size_t)nxt.pm * tstep : cA; const char* nB = has_next ? (const char*)g.Bt + (size_t)nxt.pn * tstep : cB;
;         for (int t = 0; t < nt; t += 2) {
;             const bool last = (t == nt - 2);
;             const char* a1 = cA + (size_t)(t + 1) * kstep;
;             const char* a2 = last ? nA : cA + (size_t)(t + 2) * kstep; const char* b2 = last ? nB : cB + (size_t)(t + 2) * kstep;
;             const char* a3 = a2 + kstep; const char* b3 = b2 + kstep;
;             if (last && has_next) S.a_ready(nxt);
;             if constexpr (SP2) {
;             PG8_LDB(B0, 0, 0); PG8_LDB(B1, 0, 1); PG8_SCHED; PG8_LDA(At, 0, 0); PG8_STAGE(PG8_SA(1, 1), a1 + hstep, voffA);
;             PG8_WAIT_V(8); PG8_WAIT_L(0); PG8_BAR; PG8_MMA(0, 0, At, B0); PG8_MMA(0, 1, At, B1); PG8_BAR; PG8_SCHED;
;             PG8_LDA(At, 0, 1); PG8_STAGE(PG8_SB(0, 0), b2, voffB); PG8_STAGE(PG8_SB(0, 1), b2 + hstep, voffB); PG8_STAGE(PG8_SA(0, 0), a2, voffA);
;             PG8_WAIT_V(8); PG8_WAIT_L(0); PG8_BAR; PG8_MMA(1, 0, At, B0); PG8_MMA(1, 1, At, B1); PG8_BAR; PG8_SCHED;
;     ...
;         for (int a = 0; a < 2; ++a)
; #pragma unroll
;             for (int b = 0; b < 2; ++b)
; #pragma unroll
;                 for (int m = 0; m < 4; ++m)
; #pragma unroll
;                     for (int n = 0; n < 2; ++n) acc[a][b][m][n] = (f32x4){0.f, 0.f, 0.f, 0.f};
.LBB0_174:
	s_ashr_i32 s39, s38, 31
	s_lshl_b64 s[0:1], s[38:39], 19
	s_add_u32 s48, s23, s0
	s_addc_u32 s49, s12, s1
	s_and_b64 s[0:1], s[42:43], exec
	s_cselect_b32 s0, s49, s57
	s_cselect_b32 s1, s48, s56
	s_ashr_i32 s37, s36, 31
	s_lshl_b64 s[24:25], s[36:37], 19
	s_add_u32 s52, s85, s24
	s_addc_u32 s53, s86, s25
	s_and_b64 s[24:25], s[42:43], exec
	s_cselect_b32 s10, s53, s59
	s_cselect_b32 s22, s52, s58
	s_add_u32 s56, s56, 0x40080
	s_addc_u32 s57, s57, 0
	s_add_u32 s33, s58, 0x100
	s_addc_u32 s37, s59, 0
	s_mov_b32 s39, -2
	s_waitcnt lgkmcnt(0)
	s_add_u32 s24, s56, 0xfffc0080
	s_addc_u32 s25, s57, -1
	s_add_i32 s45, 0, 0x10000
	s_cmp_eq_u32 s39, 12
	s_cselect_b32 s61, s0, s25
	s_cselect_b32 s60, s1, s24
	v_add_u32_e32 v132, s45, v192
	s_cselect_b32 s59, s10, s37
	s_cselect_b32 s58, s22, s33
	s_add_i32 s47, 0, 0x14000
	ds_read_b128 v[128:131], v132
	ds_read_b128 v[158:161], v132 offset:1024
	ds_read_b128 v[162:165], v132 offset:2048
	ds_read_b128 v[166:169], v132 offset:3072
	v_add_u32_e32 v132, s47, v192
	ds_read_b128 v[194:197], v132
	ds_read_b128 v[198:201], v132 offset:1024
	ds_read_b128 v[202:205], v132 offset:2048
	ds_read_b128 v[206:209], v132 offset:3072
	v_lshl_add_u64 v[170:171], s[56:57], 0, v[154:155]
	s_add_i32 m0, s73, 0xc000
	ds_read_b128 v[210:213], v193
	ds_read_b128 v[214:217], v193 offset:1024
	ds_read_b128 v[218:221], v193 offset:2048
	ds_read_b128 v[222:225], v193 offset:3072
	ds_read_b128 v[226:229], v193 offset:4096
	ds_read_b128 v[230:233], v193 offset:5120
	ds_read_b128 v[234:237], v193 offset:6144
	ds_read_b128 v[238:241], v193 offset:7168
	global_load_lds_dwordx4 v[170:171], off
	v_lshl_add_u64 v[170:171], s[56:57], 0, v[156:157]
	s_add_i32 m0, s73, 0xe000
	s_nop 0
	global_load_lds_dwordx4 v[170:171], off
	s_waitcnt vmcnt(8)
	s_waitcnt lgkmcnt(0)
	s_barrier
	s_setprio 1
	s_waitcnt lgkmcnt(0)
	v_mfma_f32_16x16x32_bf16 v[124:127], v[128:131], v[210:213], 0
	v_mfma_f32_16x16x32_bf16 v[120:123], v[162:165], v[210:213], 0
	v_mfma_f32_16x16x32_bf16 v[108:111], v[128:131], v[218:221], 0
	v_mfma_f32_16x16x32_bf16 v[104:107], v[162:165], v[218:221], 0
	v_mfma_f32_16x16x32_bf16 v[92:95], v[128:131], v[226:229], 0
	v_mfma_f32_16x16x32_bf16 v[88:91], v[162:165], v[226:229], 0
	v_mfma_f32_16x16x32_bf16 v[76:79], v[128:131], v[234:237], 0
	v_mfma_f32_16x16x32_bf16 v[72:75], v[162:165], v[234:237], 0
	v_mfma_f32_16x16x32_bf16 v[124:127], v[158:161], v[214:217], v[124:127]
	v_mfma_f32_16x16x32_bf16 v[120:123], v[166:169], v[214:217], v[120:123]
	v_mfma_f32_16x16x32_bf16 v[108:111], v[158:161], v[222:225], v[108:111]
	v_mfma_f32_16x16x32_bf16 v[104:107], v[166:169], v[222:225], v[104:107]
	v_mfma_f32_16x16x32_bf16 v[92:95], v[158:161], v[230:233], v[92:95]
	v_mfma_f32_16x16x32_bf16 v[88:91], v[166:169], v[230:233], v[88:91]
	v_mfma_f32_16x16x32_bf16 v[76:79], v[158:161], v[238:241], v[76:79]
	v_mfma_f32_16x16x32_bf16 v[72:75], v[166:169], v[238:241], v[72:75]
	s_setprio 0
	s_setprio 1
	v_mfma_f32_16x16x32_bf16 v[116:119], v[194:197], v[210:213], 0
	v_mfma_f32_16x16x32_bf16 v[112:115], v[202:205], v[210:213], 0
	v_mfma_f32_16x16x32_bf16 v[100:103], v[194:197], v[218:221], 0
	v_mfma_f32_16x16x32_bf16 v[96:99], v[202:205], v[218:221], 0
	v_mfma_f32_16x16x32_bf16 v[84:87], v[194:197], v[226:229], 0
	v_mfma_f32_16x16x32_bf16 v[80:83], v[202:205], v[226:229], 0
	v_mfma_f32_16x16x32_bf16 v[68:71], v[194:197], v[234:237], 0
	v_mfma_f32_16x16x32_bf16 v[64:67], v[202:205], v[234:237], 0
	v_mfma_f32_16x16x32_bf16 v[116:119], v[198:201], v[214:217], v[116:119]
	v_mfma_f32_16x16x32_bf16 v[112:115], v[206:209], v[214:217], v[112:115]
	v_mfma_f32_16x16x32_bf16 v[100:103], v[198:201], v[222:225], v[100:103]
	v_mfma_f32_16x16x32_bf16 v[96:99], v[206:209], v[222:225], v[96:99]
	v_mfma_f32_16x16x32_bf16 v[84:87], v[198:201], v[230:233], v[84:87]
	v_mfma_f32_16x16x32_bf16 v[80:83], v[206:209], v[230:233], v[80:83]
	v_mfma_f32_16x16x32_bf16 v[68:71], v[198:201], v[238:241], v[68:71]
	v_mfma_f32_16x16x32_bf16 v[64:67], v[206:209], v[238:241], v[64:67]
	s_setprio 0
	s_barrier
	s_add_i32 s24, s45, s29
	v_lshl_add_u64 v[170:171], s[58:59], 0, v[142:143]
	s_mov_b32 m0, s24
	ds_read_b128 v[210:213], v193 offset:16384
	ds_read_b128 v[214:217], v193 offset:17408
	ds_read_b128 v[218:221], v193 offset:18432
	ds_read_b128 v[222:225], v193 offset:19456
	ds_read_b128 v[226:229], v193 offset:20480
	ds_read_b128 v[230:233], v193 offset:21504
	ds_read_b128 v[234:237], v193 offset:22528
	ds_read_b128 v[238:241], v193 offset:23552
	global_load_lds_dwordx4 v[170:171], off
	s_add_i32 m0, s24, 0x2000
	s_add_u32 s24, s58, 0x40000
	v_lshl_add_u64 v[242:243], s[58:59], 0, v[146:147]
	s_addc_u32 s25, s59, 0
	s_add_i32 s45, s47, s29
	global_load_lds_dwordx4 v[242:243], off
	v_lshl_add_u64 v[244:245], s[24:25], 0, v[142:143]
	s_mov_b32 m0, s45
	v_lshl_add_u64 v[246:247], s[60:61], 0, v[144:145]
	global_load_lds_dwordx4 v[244:245], off
	v_lshl_add_u64 v[244:245], s[24:25], 0, v[146:147]
	s_add_i32 m0, s45, 0x2000
	s_nop 0
	global_load_lds_dwordx4 v[244:245], off
	v_lshl_add_u64 v[244:245], s[60:61], 0, v[140:141]
	s_mov_b32 m0, s73
	s_nop 0
	global_load_lds_dwordx4 v[244:245], off
	s_mov_b32 m0, s87
	s_nop 0
	global_load_lds_dwordx4 v[246:247], off
	s_waitcnt vmcnt(8)
	s_waitcnt lgkmcnt(0)
	s_barrier
; #define PG8_STAGE(bufoff, gbase, voff) do { _Pragma("unroll") for (int _i = 0; _i < 2; ++_i) \
;         __builtin_amdgcn_global_load_lds((const unsigned*)((const char*)(gbase) + (voff)[_i]), (PG8_LAS unsigned*)(lds + (bufoff) + ldsw + _i * 8192), 16, 0, 0); } while (0)
; #define PG8_LDA(dst, b, h) do { _Pragma("unroll") for (int m = 0; m < 4; ++m) _Pragma("unroll") for (int k = 0; k < 2; ++k) dst[m][k] = *(const PG8_LAS bf16x8*)(lds + PG8_SA(b, h) + aoff + m * 2048 + k * 1024); } while (0)
; #define PG8_LDB(dst, b, h) do { _Pragma("unroll") for (int n = 0; n < 2; ++n) _Pragma("unroll") for (int k = 0; k < 2; ++k) dst[n][k] = *(const PG8_LAS bf16x8*)(lds + PG8_SB(b, h) + boff + n * 2048 + k * 1024); } while (0)
; #define PG8_MMA(ai, bj, At, Bt) do { __builtin_amdgcn_s_setprio(1); _Pragma("unroll") for (int m = 0; m < 4; ++m) _Pragma("unroll") for (int n = 0; n < 2; ++n) _Pragma("unroll") for (int k = 0; k < 2; ++k) \
;         acc[ai][bj][m][n] = __builtin_amdgcn_mfma_f32_16x16x32_bf16(Bt[n][k], At[m][k], acc[ai][bj][m][n], 0, 0, 0); __builtin_amdgcn_s_setprio(0); } while (0)
; #define PG8_WAIT_V(n) asm volatile("s_waitcnt vmcnt(" #n ")" ::: "memory")
; #define PG8_WAIT_L(n) asm volatile("s_waitcnt lgkmcnt(" #n ")" ::: "memory")
; #define PG8_BAR __builtin_amdgcn_s_barrier()
; #define PG8_SCHED __builtin_amdgcn_sched_barrier(0)
; template <class Epi, class Sched, bool ALIGN_EPI = false, bool SP2 = false>
; __device__ __forceinline__ void gemm_phase(PG8_LAS unsigned char* lds, const Gemm g, const Sched& S, const Epi& E) {
;     ...
;             PG8_WAIT_V(8); PG8_WAIT_L(0); PG8_BAR; PG8_MMA(1, 0, At, B0); PG8_MMA(1, 1, At, B1); PG8_BAR; PG8_SCHED;
;             PG8_LDB(B0, 1, 0); PG8_LDB(B1, 1, 1); PG8_SCHED; PG8_LDA(At, 1, 0); PG8_STAGE(PG8_SA(0, 1), a2 + hstep, voffA);
;             PG8_WAIT_V(8); PG8_WAIT_L(0); PG8_BAR; PG8_MMA(0, 0, At, B0); PG8_MMA(0, 1, At, B1); PG8_BAR; PG8_SCHED;
;             PG8_LDA(At, 1, 1); PG8_STAGE(PG8_SB(1, 0), b3, voffB); PG8_STAGE(PG8_SB(1, 1), b3 + hstep, voffB); PG8_STAGE(PG8_SA(1, 0), a3, voffA);
;             PG8_WAIT_V(8); PG8_WAIT_L(0); PG8_BAR; PG8_MMA(1, 0, At, B0); PG8_MMA(1, 1, At, B1); PG8_BAR; PG8_SCHED;
	s_setprio 1
	s_waitcnt lgkmcnt(0)
	v_mfma_f32_16x16x32_bf16 v[60:63], v[128:131], v[210:213], 0
	v_mfma_f32_16x16x32_bf16 v[56:59], v[162:165], v[210:213], 0
	v_mfma_f32_16x16x32_bf16 v[44:47], v[128:131], v[218:221], 0
	v_mfma_f32_16x16x32_bf16 v[40:43], v[162:165], v[218:221], 0
	v_mfma_f32_16x16x32_bf16 v[28:31], v[128:131], v[226:229], 0
	v_mfma_f32_16x16x32_bf16 v[24:27], v[162:165], v[226:229], 0
	v_mfma_f32_16x16x32_bf16 v[12:15], v[128:131], v[234:237], 0
	v_mfma_f32_16x16x32_bf16 v[8:11], v[162:165], v[234:237], 0
	v_mfma_f32_16x16x32_bf16 v[60:63], v[158:161], v[214:217], v[60:63]
	v_mfma_f32_16x16x32_bf16 v[56:59], v[166:169], v[214:217], v[56:59]
	v_mfma_f32_16x16x32_bf16 v[44:47], v[158:161], v[222:225], v[44:47]
	v_mfma_f32_16x16x32_bf16 v[40:43], v[166:169], v[222:225], v[40:43]
	v_mfma_f32_16x16x32_bf16 v[28:31], v[158:161], v[230:233], v[28:31]
	v_mfma_f32_16x16x32_bf16 v[24:27], v[166:169], v[230:233], v[24:27]
	v_mfma_f32_16x16x32_bf16 v[12:15], v[158:161], v[238:241], v[12:15]
	v_mfma_f32_16x16x32_bf16 v[8:11], v[166:169], v[238:241], v[8:11]
	s_setprio 0
	s_setprio 1
	v_mfma_f32_16x16x32_bf16 v[52:55], v[194:197], v[210:213], 0
	v_mfma_f32_16x16x32_bf16 v[48:51], v[202:205], v[210:213], 0
	v_mfma_f32_16x16x32_bf16 v[36:39], v[194:197], v[218:221], 0
	v_mfma_f32_16x16x32_bf16 v[32:35], v[202:205], v[218:221], 0
	v_mfma_f32_16x16x32_bf16 v[20:23], v[194:197], v[226:229], 0
	v_mfma_f32_16x16x32_bf16 v[16:19], v[202:205], v[226:229], 0
	v_mfma_f32_16x16x32_bf16 v[4:7], v[194:197], v[234:237], 0
	v_mfma_f32_16x16x32_bf16 v[0:3], v[202:205], v[234:237], 0
	v_mfma_f32_16x16x32_bf16 v[52:55], v[198:201], v[214:217], v[52:55]
	v_mfma_f32_16x16x32_bf16 v[48:51], v[206:209], v[214:217], v[48:51]
	v_mfma_f32_16x16x32_bf16 v[36:39], v[198:201], v[222:225], v[36:39]
	v_mfma_f32_16x16x32_bf16 v[32:35], v[206:209], v[222:225], v[32:35]
	v_mfma_f32_16x16x32_bf16 v[20:23], v[198:201], v[230:233], v[20:23]
	v_mfma_f32_16x16x32_bf16 v[16:19], v[206:209], v[230:233], v[16:19]
	v_mfma_f32_16x16x32_bf16 v[4:7], v[198:201], v[238:241], v[4:7]
	v_mfma_f32_16x16x32_bf16 v[0:3], v[206:209], v[238:241], v[0:3]
	s_setprio 0
	s_barrier
	s_add_i32 s45, 0, 0x18000
	v_add_u32_e32 v132, s45, v192
	s_add_i32 s47, 0, 0x1c000
	ds_read_b128 v[128:131], v132
	ds_read_b128 v[158:161], v132 offset:1024
	ds_read_b128 v[162:165], v132 offset:2048
	ds_read_b128 v[166:169], v132 offset:3072
	v_add_u32_e32 v132, s47, v192
	ds_read_b128 v[194:197], v132
	ds_read_b128 v[198:201], v132 offset:1024
	ds_read_b128 v[202:205], v132 offset:2048
	ds_read_b128 v[206:209], v132 offset:3072
	s_add_u32 s24, s60, 0x40000
	s_addc_u32 s25, s61, 0
	s_mov_b32 m0, s88
	v_lshl_add_u64 v[248:249], s[24:25], 0, v[140:141]
	ds_read_b128 v[210:213], v193 offset:32768
	ds_read_b128 v[214:217], v193 offset:33792
	ds_read_b128 v[218:221], v193 offset:34816
	ds_read_b128 v[222:225], v193 offset:35840
	ds_read_b128 v[226:229], v193 offset:36864
	ds_read_b128 v[230:233], v193 offset:37888
	ds_read_b128 v[234:237], v193 offset:38912
	ds_read_b128 v[238:241], v193 offset:39936
	global_load_lds_dwordx4 v[248:249], off
	v_lshl_add_u64 v[248:249], s[24:25], 0, v[144:145]
	s_mov_b32 m0, s89
	s_nop 0
	global_load_lds_dwordx4 v[248:249], off
	s_waitcnt vmcnt(8)
	s_waitcnt lgkmcnt(0)
	s_barrier
	s_setprio 1
	s_waitcnt lgkmcnt(0)
	v_mfma_f32_16x16x32_bf16 v[124:127], v[128:131], v[210:213], v[124:127]
	v_mfma_f32_16x16x32_bf16 v[120:123], v[162:165], v[210:213], v[120:123]
	v_mfma_f32_16x16x32_bf16 v[108:111], v[128:131], v[218:221], v[108:111]
	v_mfma_f32_16x16x32_bf16 v[104:107], v[162:165], v[218:221], v[104:107]
	v_mfma_f32_16x16x32_bf16 v[92:95], v[128:131], v[226:229], v[92:95]
	v_mfma_f32_16x16x32_bf16 v[88:91], v[162:165], v[226:229], v[88:91]
	v_mfma_f32_16x16x32_bf16 v[76:79], v[128:131], v[234:237], v[76:79]
	v_mfma_f32_16x16x32_bf16 v[72:75], v[162:165], v[234:237], v[72:75]
	v_mfma_f32_16x16x32_bf16 v[124:127], v[158:161], v[214:217], v[124:127]
	v_mfma_f32_16x16x32_bf16 v[120:123], v[166:169], v[214:217], v[120:123]
	v_mfma_f32_16x16x32_bf16 v[108:111], v[158:161], v[222:225], v[108:111]
	v_mfma_f32_16x16x32_bf16 v[104:107], v[166:169], v[222:225], v[104:107]
	v_mfma_f32_16x16x32_bf16 v[92:95], v[158:161], v[230:233], v[92:95]
	v_mfma_f32_16x16x32_bf16 v[88:91], v[166:169], v[230:233], v[88:91]
	v_mfma_f32_16x16x32_bf16 v[76:79], v[158:161], v[238:241], v[76:79]
	v_mfma_f32_16x16x32_bf16 v[72:75], v[166:169], v[238:241], v[72:75]
	s_setprio 0
	s_setprio 1
	v_mfma_f32_16x16x32_bf16 v[116:119], v[194:197], v[210:213], v[116:119]
	v_mfma_f32_16x16x32_bf16 v[112:115], v[202:205], v[210:213], v[112:115]
	v_mfma_f32_16x16x32_bf16 v[100:103], v[194:197], v[218:221], v[100:103]
	v_mfma_f32_16x16x32_bf16 v[96:99], v[202:205], v[218:221], v[96:99]
	v_mfma_f32_16x16x32_bf16 v[84:87], v[194:197], v[226:229], v[84:87]
	v_mfma_f32_16x16x32_bf16 v[80:83], v[202:205], v[226:229], v[80:83]
	v_mfma_f32_16x16x32_bf16 v[68:71], v[194:197], v[234:237], v[68:71]
	v_mfma_f32_16x16x32_bf16 v[64:67], v[202:205], v[234:237], v[64:67]
	v_mfma_f32_16x16x32_bf16 v[116:119], v[198:201], v[214:217], v[116:119]
	v_mfma_f32_16x16x32_bf16 v[112:115], v[206:209], v[214:217], v[112:115]
	v_mfma_f32_16x16x32_bf16 v[100:103], v[198:201], v[222:225], v[100:103]
	v_mfma_f32_16x16x32_bf16 v[96:99], v[206:209], v[222:225], v[96:99]
	v_mfma_f32_16x16x32_bf16 v[84:87], v[198:201], v[230:233], v[84:87]
	v_mfma_f32_16x16x32_bf16 v[80:83], v[206:209], v[230:233], v[80:83]
	v_mfma_f32_16x16x32_bf16 v[68:71], v[198:201], v[238:241], v[68:71]
	v_mfma_f32_16x16x32_bf16 v[64:67], v[206:209], v[238:241], v[64:67]
	s_setprio 0
	s_barrier
; #define PG8_STAGE(bufoff, gbase, voff) do { _Pragma("unroll") for (int _i = 0; _i < 2; ++_i) \
;         __builtin_amdgcn_global_load_lds((const unsigned*)((const char*)(gbase) + (voff)[_i]), (PG8_LAS unsigned*)(lds + (bufoff) + ldsw + _i * 8192), 16, 0, 0); } while (0)
; #define PG8_LDA(dst, b, h) do { _Pragma("unroll") for (int m = 0; m < 4; ++m) _Pragma("unroll") for (int k = 0; k < 2; ++k) dst[m][k] = *(const PG8_LAS bf16x8*)(lds + PG8_SA(b, h) + aoff + m * 2048 + k * 1024); } while (0)
; #define PG8_LDB(dst, b, h) do { _Pragma("unroll") for (int n = 0; n < 2; ++n) _Pragma("unroll") for (int k = 0; k < 2; ++k) dst[n][k] = *(const PG8_LAS bf16x8*)(lds + PG8_SB(b, h) + boff + n * 2048 + k * 1024); } while (0)
; #define PG8_MMA(ai, bj, At, Bt) do { __builtin_amdgcn_s_setprio(1); _Pragma("unroll") for (int m = 0; m < 4; ++m) _Pragma("unroll") for (int n = 0; n < 2; ++n) _Pragma("unroll") for (int k = 0; k < 2; ++k) \
;         acc[ai][bj][m][n] = __builtin_amdgcn_mfma_f32_16x16x32_bf16(Bt[n][k], At[m][k], acc[ai][bj][m][n], 0, 0, 0); __builtin_amdgcn_s_setprio(0); } while (0)
; #define PG8_WAIT_V(n) asm volatile("s_waitcnt vmcnt(" #n ")" ::: "memory")
; #define PG8_WAIT_L(n) asm volatile("s_waitcnt lgkmcnt(" #n ")" ::: "memory")
; #define PG8_BAR __builtin_amdgcn_s_barrier()
; template <class Epi, class Sched, bool ALIGN_EPI = false, bool SP2 = false>
; __device__ __forceinline__ void gemm_phase(PG8_LAS unsigned char* lds, const Gemm g, const Sched& S, const Epi& E) {
;     ...
;         for (int t = 0; t < nt; t += 2) {
;             const bool last = (t == nt - 2);
;             const char* a1 = cA + (size_t)(t + 1) * kstep;
;             const char* a2 = last ? nA : cA + (size_t)(t + 2) * kstep; const char* b2 = last ? nB : cB + (size_t)(t + 2) * kstep;
;             const char* a3 = a2 + kstep; const char* b3 = b2 + kstep;
;     ...
;             PG8_LDB(B0, 1, 0); PG8_LDB(B1, 1, 1); PG8_SCHED; PG8_LDA(At, 1, 0); PG8_STAGE(PG8_SA(0, 1), a2 + hstep, voffA);
;             PG8_WAIT_V(8); PG8_WAIT_L(0); PG8_BAR; PG8_MMA(0, 0, At, B0); PG8_MMA(0, 1, At, B1); PG8_BAR; PG8_SCHED;
;             PG8_LDA(At, 1, 1); PG8_STAGE(PG8_SB(1, 0), b3, voffB); PG8_STAGE(PG8_SB(1, 1), b3 + hstep, voffB); PG8_STAGE(PG8_SA(1, 0), a3, voffA);
;             PG8_WAIT_V(8); PG8_WAIT_L(0); PG8_BAR; PG8_MMA(1, 0, At, B0); PG8_MMA(1, 1, At, B1); PG8_BAR; PG8_SCHED;
	s_add_i32 s24, s45, s29
	v_lshl_add_u64 v[170:171], v[170:171], 0, s[14:15]
	s_mov_b32 m0, s24
	ds_read_b128 v[210:213], v193 offset:49152
	ds_read_b128 v[214:217], v193 offset:50176
	ds_read_b128 v[218:221], v193 offset:51200
	ds_read_b128 v[222:225], v193 offset:52224
	ds_read_b128 v[226:229], v193 offset:53248
	ds_read_b128 v[230:233], v193 offset:54272
	ds_read_b128 v[234:237], v193 offset:55296
	ds_read_b128 v[238:241], v193 offset:56320
	global_load_lds_dwordx4 v[170:171], off
	s_add_i32 m0, s24, 0x2000
	s_add_u32 s24, s58, 0x40080
	v_lshl_add_u64 v[170:171], v[242:243], 0, s[14:15]
	s_addc_u32 s25, s59, 0
	s_add_i32 s45, s47, s29
	global_load_lds_dwordx4 v[170:171], off
	v_lshl_add_u64 v[170:171], s[24:25], 0, v[142:143]
	s_mov_b32 m0, s45
	s_nop 0
	global_load_lds_dwordx4 v[170:171], off
	v_lshl_add_u64 v[170:171], s[24:25], 0, v[146:147]
	s_add_i32 m0, s45, 0x2000
	s_nop 0
	global_load_lds_dwordx4 v[170:171], off
	v_lshl_add_u64 v[170:171], v[244:245], 0, s[14:15]
	s_mov_b32 m0, s90
	s_nop 0
	global_load_lds_dwordx4 v[170:171], off
	v_lshl_add_u64 v[170:171], v[246:247], 0, s[14:15]
	s_mov_b32 m0, s91
	s_nop 0
	global_load_lds_dwordx4 v[170:171], off
	s_waitcnt vmcnt(8)
	s_waitcnt lgkmcnt(0)
	s_barrier
	s_setprio 1
	s_waitcnt lgkmcnt(0)
	v_mfma_f32_16x16x32_bf16 v[60:63], v[128:131], v[210:213], v[60:63]
	v_mfma_f32_16x16x32_bf16 v[56:59], v[162:165], v[210:213], v[56:59]
	v_mfma_f32_16x16x32_bf16 v[44:47], v[128:131], v[218:221], v[44:47]
	v_mfma_f32_16x16x32_bf16 v[40:43], v[162:165], v[218:221], v[40:43]
	v_mfma_f32_16x16x32_bf16 v[28:31], v[128:131], v[226:229], v[28:31]
	v_mfma_f32_16x16x32_bf16 v[24:27], v[162:165], v[226:229], v[24:27]
	v_mfma_f32_16x16x32_bf16 v[12:15], v[128:131], v[234:237], v[12:15]
	v_mfma_f32_16x16x32_bf16 v[8:11], v[162:165], v[234:237], v[8:11]
	v_mfma_f32_16x16x32_bf16 v[60:63], v[158:161], v[214:217], v[60:63]
	v_mfma_f32_16x16x32_bf16 v[56:59], v[166:169], v[214:217], v[56:59]
	v_mfma_f32_16x16x32_bf16 v[44:47], v[158:161], v[222:225], v[44:47]
	v_mfma_f32_16x16x32_bf16 v[40:43], v[166:169], v[222:225], v[40:43]
	v_mfma_f32_16x16x32_bf16 v[28:31], v[158:161], v[230:233], v[28:31]
	v_mfma_f32_16x16x32_bf16 v[24:27], v[166:169], v[230:233], v[24:27]
	v_mfma_f32_16x16x32_bf16 v[12:15], v[158:161], v[238:241], v[12:15]
	v_mfma_f32_16x16x32_bf16 v[8:11], v[166:169], v[238:241], v[8:11]
	s_setprio 0
	s_setprio 1
	v_mfma_f32_16x16x32_bf16 v[52:55], v[194:197], v[210:213], v[52:55]
	v_mfma_f32_16x16x32_bf16 v[48:51], v[202:205], v[210:213], v[48:51]
	v_mfma_f32_16x16x32_bf16 v[36:39], v[194:197], v[218:221], v[36:39]
	v_mfma_f32_16x16x32_bf16 v[32:35], v[202:205], v[218:221], v[32:35]
	v_mfma_f32_16x16x32_bf16 v[20:23], v[194:197], v[226:229], v[20:23]
	v_mfma_f32_16x16x32_bf16 v[16:19], v[202:205], v[226:229], v[16:19]
	v_mfma_f32_16x16x32_bf16 v[4:7], v[194:197], v[234:237], v[4:7]
	v_mfma_f32_16x16x32_bf16 v[0:3], v[202:205], v[234:237], v[0:3]
	v_mfma_f32_16x16x32_bf16 v[52:55], v[198:201], v[214:217], v[52:55]
	v_mfma_f32_16x16x32_bf16 v[48:51], v[206:209], v[214:217], v[48:51]
	v_mfma_f32_16x16x32_bf16 v[36:39], v[198:201], v[222:225], v[36:39]
	v_mfma_f32_16x16x32_bf16 v[32:35], v[206:209], v[222:225], v[32:35]
	v_mfma_f32_16x16x32_bf16 v[20:23], v[198:201], v[230:233], v[20:23]
	v_mfma_f32_16x16x32_bf16 v[16:19], v[206:209], v[230:233], v[16:19]
	v_mfma_f32_16x16x32_bf16 v[4:7], v[198:201], v[238:241], v[4:7]
	v_mfma_f32_16x16x32_bf16 v[0:3], v[206:209], v[238:241], v[0:3]
	s_setprio 0
	s_barrier
	s_add_i32 s39, s39, 2
	s_add_u32 s56, s56, 0x100
	s_addc_u32 s57, s57, 0
	s_add_u32 s33, s33, 0x100
	s_addc_u32 s37, s37, 0
	s_cmp_gt_u32 s39, 13

; #define PG8_STAGE(bufoff, gbase, voff) do { _Pragma("unroll") for (int _i = 0; _i < 2; ++_i) \
;         __builtin_amdgcn_global_load_lds((const unsigned*)((const char*)(gbase) + (voff)[_i]), (PG8_LAS unsigned*)(lds + (bufoff) + ldsw + _i * 8192), 16, 0, 0); } while (0)
; #define PG8_LDA(dst, b, h) do { _Pragma("unroll") for (int m = 0; m < 4; ++m) _Pragma("unroll") for (int k = 0; k < 2; ++k) dst[m][k] = *(const PG8_LAS bf16x8*)(lds + PG8_SA(b, h) + aoff + m * 2048 + k * 1024); } while (0)
; #define PG8_LDB(dst, b, h) do { _Pragma("unroll") for (int n = 0; n < 2; ++n) _Pragma("unroll") for (int k = 0; k < 2; ++k) dst[n][k] = *(const PG8_LAS bf16x8*)(lds + PG8_SB(b, h) + boff + n * 2048 + k * 1024); } while (0)
; template <class Epi, class Sched, bool ALIGN_EPI = false, bool SP2 = false>
; __device__ __forceinline__ void gemm_phase(PG8_LAS unsigned char* lds, const Gemm g, const Sched& S, const Epi& E) {
;     ...
;         const bool has_next = S.next(ui + 1, nxt);
;         const char* nA = has_next ? (const char*)g.A + (size_t)nxt.pm * tstep : cA; const char* nB = has_next ? (const char*)g.Bt + (size_t)nxt.pn * tstep : cB;
;         for (int t = 0; t < nt; t += 2) {
;             const bool last = (t == nt - 2);
;             const char* a1 = cA + (size_t)(t + 1) * kstep;
;             const char* a2 = last ? nA : cA + (size_t)(t + 2) * kstep; const char* b2 = last ? nB : cB + (size_t)(t + 2) * kstep;
;             const char* a3 = a2 + kstep; const char* b3 = b2 + kstep;
;             if (last && has_next) S.a_ready(nxt);
;             if constexpr (SP2) {
;             PG8_LDB(B0, 0, 0); PG8_LDB(B1, 0, 1); PG8_SCHED; PG8_LDA(At, 0, 0); PG8_STAGE(PG8_SA(1, 1), a1 + hstep, voffA);
;             PG8_WAIT_V(8); PG8_WAIT_L(0); PG8_BAR; PG8_MMA(0, 0, At, B0); PG8_MMA(0, 1, At, B1); PG8_BAR; PG8_SCHED;
;             PG8_LDA(At, 0, 1); PG8_STAGE(PG8_SB(0, 0), b2, voffB); PG8_STAGE(PG8_SB(0, 1), b2 + hstep, voffB); PG8_STAGE(PG8_SA(0, 0), a2, voffA);
;             PG8_WAIT_V(8); PG8_WAIT_L(0); PG8_BAR; PG8_MMA(1, 0, At, B0); PG8_MMA(1, 1, At, B1); PG8_BAR; PG8_SCHED;
;     ...
;         for (int a = 0; a < 2; ++a)
; #pragma unroll
;             for (int b = 0; b < 2; ++b)
; #pragma unroll
;                 for (int m = 0; m < 4; ++m)
; #pragma unroll
;                     for (int n = 0; n < 2; ++n) acc[a][b][m][n] = (f32x4){0.f, 0.f, 0.f, 0.f};
.LBB0_553:
	s_ashr_i32 s21, s20, 31
	s_lshl_b64 s[0:1], s[20:21], 19
	s_add_u32 s38, s26, s0
	s_addc_u32 s39, s27, s1
	s_and_b64 s[0:1], s[42:43], exec
	s_cselect_b32 s0, s39, s57
	s_cselect_b32 s1, s38, s56
	s_ashr_i32 s17, s16, 31
	s_lshl_b64 s[24:25], s[16:17], 19
	s_add_u32 s48, s10, s24
	s_addc_u32 s49, s12, s25
	s_and_b64 s[24:25], s[42:43], exec
	s_cselect_b32 s17, s49, s59
	s_cselect_b32 s21, s48, s58
	s_add_u32 s56, s56, 0x40080
	s_addc_u32 s57, s57, 0
	s_add_u32 s22, s58, 0x100
	s_addc_u32 s33, s59, 0
	s_mov_b32 s45, -2
	s_add_u32 s24, s56, 0xfffc0080
	s_addc_u32 s25, s57, -1
	s_add_i32 s47, 0, 0x10000
	s_cmp_eq_u32 s45, 12
	s_cselect_b32 s61, s0, s25
	s_cselect_b32 s60, s1, s24
	s_cselect_b32 s59, s17, s33
	s_cselect_b32 s58, s21, s22
	s_add_i32 s50, 0, 0x14000
	v_add_u32_e32 v162, s47, v159
	v_add_u32_e32 v170, s50, v159
	ds_read_b128 v[146:149], v162
	ds_read_b128 v[150:153], v162 offset:1024
	ds_read_b128 v[154:157], v162 offset:2048
	ds_read_b128 v[162:165], v162 offset:3072
	ds_read_b128 v[166:169], v170
	ds_read_b128 v[192:195], v170 offset:1024
	ds_read_b128 v[196:199], v170 offset:2048
	ds_read_b128 v[200:203], v170 offset:3072
	v_lshl_add_u64 v[170:171], s[56:57], 0, v[142:143]
	s_add_i32 m0, s29, 0xc000
	ds_read_b128 v[204:207], v161
	ds_read_b128 v[208:211], v161 offset:1024
	ds_read_b128 v[212:215], v161 offset:2048
	ds_read_b128 v[216:219], v161 offset:3072
	ds_read_b128 v[220:223], v161 offset:4096
	ds_read_b128 v[224:227], v161 offset:5120
	ds_read_b128 v[228:231], v161 offset:6144
	ds_read_b128 v[232:235], v161 offset:7168
	global_load_lds_dwordx4 v[170:171], off
	v_lshl_add_u64 v[170:171], s[56:57], 0, v[144:145]
	s_add_i32 m0, s29, 0xe000
	s_nop 0
	global_load_lds_dwordx4 v[170:171], off
	s_waitcnt vmcnt(8)
	s_waitcnt lgkmcnt(0)
	s_barrier
	s_setprio 1
	s_waitcnt lgkmcnt(0)
	v_mfma_f32_16x16x32_bf16 v[124:127], v[146:149], v[204:207], 0
	v_mfma_f32_16x16x32_bf16 v[120:123], v[154:157], v[204:207], 0
	v_mfma_f32_16x16x32_bf16 v[108:111], v[146:149], v[212:215], 0
	v_mfma_f32_16x16x32_bf16 v[104:107], v[154:157], v[212:215], 0
	v_mfma_f32_16x16x32_bf16 v[92:95], v[146:149], v[220:223], 0
	v_mfma_f32_16x16x32_bf16 v[88:91], v[154:157], v[220:223], 0
	v_mfma_f32_16x16x32_bf16 v[76:79], v[146:149], v[228:231], 0
	v_mfma_f32_16x16x32_bf16 v[72:75], v[154:157], v[228:231], 0
	v_mfma_f32_16x16x32_bf16 v[124:127], v[150:153], v[208:211], v[124:127]
	v_mfma_f32_16x16x32_bf16 v[120:123], v[162:165], v[208:211], v[120:123]
	v_mfma_f32_16x16x32_bf16 v[108:111], v[150:153], v[216:219], v[108:111]
	v_mfma_f32_16x16x32_bf16 v[104:107], v[162:165], v[216:219], v[104:107]
	v_mfma_f32_16x16x32_bf16 v[92:95], v[150:153], v[224:227], v[92:95]
	v_mfma_f32_16x16x32_bf16 v[88:91], v[162:165], v[224:227], v[88:91]
	v_mfma_f32_16x16x32_bf16 v[76:79], v[150:153], v[232:235], v[76:79]
	v_mfma_f32_16x16x32_bf16 v[72:75], v[162:165], v[232:235], v[72:75]
	s_setprio 0
	s_setprio 1
	v_mfma_f32_16x16x32_bf16 v[116:119], v[166:169], v[204:207], 0
	v_mfma_f32_16x16x32_bf16 v[112:115], v[196:199], v[204:207], 0
	v_mfma_f32_16x16x32_bf16 v[100:103], v[166:169], v[212:215], 0
	v_mfma_f32_16x16x32_bf16 v[96:99], v[196:199], v[212:215], 0
	v_mfma_f32_16x16x32_bf16 v[84:87], v[166:169], v[220:223], 0
	v_mfma_f32_16x16x32_bf16 v[80:83], v[196:199], v[220:223], 0
	v_mfma_f32_16x16x32_bf16 v[68:71], v[166:169], v[228:231], 0
	v_mfma_f32_16x16x32_bf16 v[64:67], v[196:199], v[228:231], 0
	v_mfma_f32_16x16x32_bf16 v[116:119], v[192:195], v[208:211], v[116:119]
	v_mfma_f32_16x16x32_bf16 v[112:115], v[200:203], v[208:211], v[112:115]
	v_mfma_f32_16x16x32_bf16 v[100:103], v[192:195], v[216:219], v[100:103]
	v_mfma_f32_16x16x32_bf16 v[96:99], v[200:203], v[216:219], v[96:99]
	v_mfma_f32_16x16x32_bf16 v[84:87], v[192:195], v[224:227], v[84:87]
	v_mfma_f32_16x16x32_bf16 v[80:83], v[200:203], v[224:227], v[80:83]
	v_mfma_f32_16x16x32_bf16 v[68:71], v[192:195], v[232:235], v[68:71]
	v_mfma_f32_16x16x32_bf16 v[64:67], v[200:203], v[232:235], v[64:67]
	s_setprio 0
	s_barrier
	s_add_i32 s24, s47, s23
	v_lshl_add_u64 v[170:171], s[58:59], 0, v[132:133]
	s_mov_b32 m0, s24
	ds_read_b128 v[204:207], v161 offset:16384
	ds_read_b128 v[208:211], v161 offset:17408
	ds_read_b128 v[212:215], v161 offset:18432
	ds_read_b128 v[216:219], v161 offset:19456
	ds_read_b128 v[220:223], v161 offset:20480
	ds_read_b128 v[224:227], v161 offset:21504
	ds_read_b128 v[228:231], v161 offset:22528
	ds_read_b128 v[232:235], v161 offset:23552
	global_load_lds_dwordx4 v[170:171], off
	s_add_i32 m0, s24, 0x2000
	s_add_u32 s24, s58, 0x40000
	v_lshl_add_u64 v[236:237], s[58:59], 0, v[140:141]
	s_addc_u32 s25, s59, 0
	s_add_i32 s47, s50, s23
	global_load_lds_dwordx4 v[236:237], off
	v_lshl_add_u64 v[238:239], s[24:25], 0, v[132:133]
	s_mov_b32 m0, s47
	v_lshl_add_u64 v[240:241], s[60:61], 0, v[130:131]
	global_load_lds_dwordx4 v[238:239], off
	v_lshl_add_u64 v[238:239], s[24:25], 0, v[140:141]
	s_add_i32 m0, s47, 0x2000
	s_nop 0
	global_load_lds_dwordx4 v[238:239], off
	v_lshl_add_u64 v[238:239], s[60:61], 0, v[128:129]
	s_mov_b32 m0, s29
	s_nop 0
	global_load_lds_dwordx4 v[238:239], off
	s_mov_b32 m0, s62
	s_nop 0
	global_load_lds_dwordx4 v[240:241], off
	s_waitcnt vmcnt(8)
	s_waitcnt lgkmcnt(0)
	s_barrier
; #define PG8_STAGE(bufoff, gbase, voff) do { _Pragma("unroll") for (int _i = 0; _i < 2; ++_i) \
;         __builtin_amdgcn_global_load_lds((const unsigned*)((const char*)(gbase) + (voff)[_i]), (PG8_LAS unsigned*)(lds + (bufoff) + ldsw + _i * 8192), 16, 0, 0); } while (0)
; #define PG8_LDA(dst, b, h) do { _Pragma("unroll") for (int m = 0; m < 4; ++m) _Pragma("unroll") for (int k = 0; k < 2; ++k) dst[m][k] = *(const PG8_LAS bf16x8*)(lds + PG8_SA(b, h) + aoff + m * 2048 + k * 1024); } while (0)
; #define PG8_LDB(dst, b, h) do { _Pragma("unroll") for (int n = 0; n < 2; ++n) _Pragma("unroll") for (int k = 0; k < 2; ++k) dst[n][k] = *(const PG8_LAS bf16x8*)(lds + PG8_SB(b, h) + boff + n * 2048 + k * 1024); } while (0)
; #define PG8_MMA(ai, bj, At, Bt) do { __builtin_amdgcn_s_setprio(1); _Pragma("unroll") for (int m = 0; m < 4; ++m) _Pragma("unroll") for (int n = 0; n < 2; ++n) _Pragma("unroll") for (int k = 0; k < 2; ++k) \
;         acc[ai][bj][m][n] = __builtin_amdgcn_mfma_f32_16x16x32_bf16(Bt[n][k], At[m][k], acc[ai][bj][m][n], 0, 0, 0); __builtin_amdgcn_s_setprio(0); } while (0)
; #define PG8_WAIT_V(n) asm volatile("s_waitcnt vmcnt(" #n ")" ::: "memory")
; #define PG8_WAIT_L(n) asm volatile("s_waitcnt lgkmcnt(" #n ")" ::: "memory")
; #define PG8_BAR __builtin_amdgcn_s_barrier()
; #define PG8_SCHED __builtin_amdgcn_sched_barrier(0)
; template <class Epi, class Sched, bool ALIGN_EPI = false, bool SP2 = false>
; __device__ __forceinline__ void gemm_phase(PG8_LAS unsigned char* lds, const Gemm g, const Sched& S, const Epi& E) {
;     ...
;             PG8_WAIT_V(8); PG8_WAIT_L(0); PG8_BAR; PG8_MMA(1, 0, At, B0); PG8_MMA(1, 1, At, B1); PG8_BAR; PG8_SCHED;
;             PG8_LDB(B0, 1, 0); PG8_LDB(B1, 1, 1); PG8_SCHED; PG8_LDA(At, 1, 0); PG8_STAGE(PG8_SA(0, 1), a2 + hstep, voffA);
;             PG8_WAIT_V(8); PG8_WAIT_L(0); PG8_BAR; PG8_MMA(0, 0, At, B0); PG8_MMA(0, 1, At, B1); PG8_BAR; PG8_SCHED;
;             PG8_LDA(At, 1, 1); PG8_STAGE(PG8_SB(1, 0), b3, voffB); PG8_STAGE(PG8_SB(1, 1), b3 + hstep, voffB); PG8_STAGE(PG8_SA(1, 0), a3, voffA);
;             PG8_WAIT_V(8); PG8_WAIT_L(0); PG8_BAR; PG8_MMA(1, 0, At, B0); PG8_MMA(1, 1, At, B1); PG8_BAR; PG8_SCHED;
	s_setprio 1
	s_waitcnt lgkmcnt(0)
	v_mfma_f32_16x16x32_bf16 v[60:63], v[146:149], v[204:207], 0
	v_mfma_f32_16x16x32_bf16 v[56:59], v[154:157], v[204:207], 0
	v_mfma_f32_16x16x32_bf16 v[44:47], v[146:149], v[212:215], 0
	v_mfma_f32_16x16x32_bf16 v[40:43], v[154:157], v[212:215], 0
	v_mfma_f32_16x16x32_bf16 v[28:31], v[146:149], v[220:223], 0
	v_mfma_f32_16x16x32_bf16 v[24:27], v[154:157], v[220:223], 0
	v_mfma_f32_16x16x32_bf16 v[12:15], v[146:149], v[228:231], 0
	v_mfma_f32_16x16x32_bf16 v[8:11], v[154:157], v[228:231], 0
	v_mfma_f32_16x16x32_bf16 v[60:63], v[150:153], v[208:211], v[60:63]
	v_mfma_f32_16x16x32_bf16 v[56:59], v[162:165], v[208:211], v[56:59]
	v_mfma_f32_16x16x32_bf16 v[44:47], v[150:153], v[216:219], v[44:47]
	v_mfma_f32_16x16x32_bf16 v[40:43], v[162:165], v[216:219], v[40:43]
	v_mfma_f32_16x16x32_bf16 v[28:31], v[150:153], v[224:227], v[28:31]
	v_mfma_f32_16x16x32_bf16 v[24:27], v[162:165], v[224:227], v[24:27]
	v_mfma_f32_16x16x32_bf16 v[12:15], v[150:153], v[232:235], v[12:15]
	v_mfma_f32_16x16x32_bf16 v[8:11], v[162:165], v[232:235], v[8:11]
	s_setprio 0
	s_setprio 1
	v_mfma_f32_16x16x32_bf16 v[52:55], v[166:169], v[204:207], 0
	v_mfma_f32_16x16x32_bf16 v[48:51], v[196:199], v[204:207], 0
	v_mfma_f32_16x16x32_bf16 v[36:39], v[166:169], v[212:215], 0
	v_mfma_f32_16x16x32_bf16 v[32:35], v[196:199], v[212:215], 0
	v_mfma_f32_16x16x32_bf16 v[20:23], v[166:169], v[220:223], 0
	v_mfma_f32_16x16x32_bf16 v[16:19], v[196:199], v[220:223], 0
	v_mfma_f32_16x16x32_bf16 v[4:7], v[166:169], v[228:231], 0
	v_mfma_f32_16x16x32_bf16 v[0:3], v[196:199], v[228:231], 0
	v_mfma_f32_16x16x32_bf16 v[52:55], v[192:195], v[208:211], v[52:55]
	v_mfma_f32_16x16x32_bf16 v[48:51], v[200:203], v[208:211], v[48:51]
	v_mfma_f32_16x16x32_bf16 v[36:39], v[192:195], v[216:219], v[36:39]
	v_mfma_f32_16x16x32_bf16 v[32:35], v[200:203], v[216:219], v[32:35]
	v_mfma_f32_16x16x32_bf16 v[20:23], v[192:195], v[224:227], v[20:23]
	v_mfma_f32_16x16x32_bf16 v[16:19], v[200:203], v[224:227], v[16:19]
	v_mfma_f32_16x16x32_bf16 v[4:7], v[192:195], v[232:235], v[4:7]
	v_mfma_f32_16x16x32_bf16 v[0:3], v[200:203], v[232:235], v[0:3]
	s_setprio 0
	s_barrier
	s_add_i32 s47, 0, 0x18000
	s_add_i32 s50, 0, 0x1c000
	v_add_u32_e32 v162, s47, v159
	v_add_u32_e32 v184, s50, v159
	ds_read_b128 v[146:149], v162
	ds_read_b128 v[150:153], v162 offset:1024
	ds_read_b128 v[154:157], v162 offset:2048
	ds_read_b128 v[162:165], v162 offset:3072
	ds_read_b128 v[166:169], v184
	ds_read_b128 v[192:195], v184 offset:1024
	ds_read_b128 v[196:199], v184 offset:2048
	ds_read_b128 v[200:203], v184 offset:3072
	s_add_u32 s24, s60, 0x40000
	s_addc_u32 s25, s61, 0
	s_mov_b32 m0, s63
	v_lshl_add_u64 v[242:243], s[24:25], 0, v[128:129]
	ds_read_b128 v[204:207], v161 offset:32768
	ds_read_b128 v[208:211], v161 offset:33792
	ds_read_b128 v[212:215], v161 offset:34816
	ds_read_b128 v[216:219], v161 offset:35840
	ds_read_b128 v[220:223], v161 offset:36864
	ds_read_b128 v[224:227], v161 offset:37888
	ds_read_b128 v[228:231], v161 offset:38912
	ds_read_b128 v[232:235], v161 offset:39936
	global_load_lds_dwordx4 v[242:243], off
	v_lshl_add_u64 v[242:243], s[24:25], 0, v[130:131]
	s_mov_b32 m0, s64
	s_nop 0
	global_load_lds_dwordx4 v[242:243], off
	s_waitcnt vmcnt(8)
	s_waitcnt lgkmcnt(0)
	s_barrier
	s_setprio 1
	s_waitcnt lgkmcnt(0)
	v_mfma_f32_16x16x32_bf16 v[124:127], v[146:149], v[204:207], v[124:127]
	v_mfma_f32_16x16x32_bf16 v[120:123], v[154:157], v[204:207], v[120:123]
	v_mfma_f32_16x16x32_bf16 v[108:111], v[146:149], v[212:215], v[108:111]
	v_mfma_f32_16x16x32_bf16 v[104:107], v[154:157], v[212:215], v[104:107]
	v_mfma_f32_16x16x32_bf16 v[92:95], v[146:149], v[220:223], v[92:95]
	v_mfma_f32_16x16x32_bf16 v[88:91], v[154:157], v[220:223], v[88:91]
	v_mfma_f32_16x16x32_bf16 v[76:79], v[146:149], v[228:231], v[76:79]
	v_mfma_f32_16x16x32_bf16 v[72:75], v[154:157], v[228:231], v[72:75]
	v_mfma_f32_16x16x32_bf16 v[124:127], v[150:153], v[208:211], v[124:127]
	v_mfma_f32_16x16x32_bf16 v[120:123], v[162:165], v[208:211], v[120:123]
	v_mfma_f32_16x16x32_bf16 v[108:111], v[150:153], v[216:219], v[108:111]
	v_mfma_f32_16x16x32_bf16 v[104:107], v[162:165], v[216:219], v[104:107]
	v_mfma_f32_16x16x32_bf16 v[92:95], v[150:153], v[224:227], v[92:95]
	v_mfma_f32_16x16x32_bf16 v[88:91], v[162:165], v[224:227], v[88:91]
	v_mfma_f32_16x16x32_bf16 v[76:79], v[150:153], v[232:235], v[76:79]
	v_mfma_f32_16x16x32_bf16 v[72:75], v[162:165], v[232:235], v[72:75]
	s_setprio 0
	s_setprio 1
	v_mfma_f32_16x16x32_bf16 v[116:119], v[166:169], v[204:207], v[116:119]
	v_mfma_f32_16x16x32_bf16 v[112:115], v[196:199], v[204:207], v[112:115]
	v_mfma_f32_16x16x32_bf16 v[100:103], v[166:169], v[212:215], v[100:103]
	v_mfma_f32_16x16x32_bf16 v[96:99], v[196:199], v[212:215], v[96:99]
	v_mfma_f32_16x16x32_bf16 v[84:87], v[166:169], v[220:223], v[84:87]
	v_mfma_f32_16x16x32_bf16 v[80:83], v[196:199], v[220:223], v[80:83]
	v_mfma_f32_16x16x32_bf16 v[68:71], v[166:169], v[228:231], v[68:71]
	v_mfma_f32_16x16x32_bf16 v[64:67], v[196:199], v[228:231], v[64:67]
	v_mfma_f32_16x16x32_bf16 v[116:119], v[192:195], v[208:211], v[116:119]
	v_mfma_f32_16x16x32_bf16 v[112:115], v[200:203], v[208:211], v[112:115]
	v_mfma_f32_16x16x32_bf16 v[100:103], v[192:195], v[216:219], v[100:103]
	v_mfma_f32_16x16x32_bf16 v[96:99], v[200:203], v[216:219], v[96:99]
	v_mfma_f32_16x16x32_bf16 v[84:87], v[192:195], v[224:227], v[84:87]
	v_mfma_f32_16x16x32_bf16 v[80:83], v[200:203], v[224:227], v[80:83]
	v_mfma_f32_16x16x32_bf16 v[68:71], v[192:195], v[232:235], v[68:71]
	v_mfma_f32_16x16x32_bf16 v[64:67], v[200:203], v[232:235], v[64:67]
	s_setprio 0
	s_barrier
; #define PG8_STAGE(bufoff, gbase, voff) do { _Pragma("unroll") for (int _i = 0; _i < 2; ++_i) \
;         __builtin_amdgcn_global_load_lds((const unsigned*)((const char*)(gbase) + (voff)[_i]), (PG8_LAS unsigned*)(lds + (bufoff) + ldsw + _i * 8192), 16, 0, 0); } while (0)
; #define PG8_LDA(dst, b, h) do { _Pragma("unroll") for (int m = 0; m < 4; ++m) _Pragma("unroll") for (int k = 0; k < 2; ++k) dst[m][k] = *(const PG8_LAS bf16x8*)(lds + PG8_SA(b, h) + aoff + m * 2048 + k * 1024); } while (0)
; #define PG8_LDB(dst, b, h) do { _Pragma("unroll") for (int n = 0; n < 2; ++n) _Pragma("unroll") for (int k = 0; k < 2; ++k) dst[n][k] = *(const PG8_LAS bf16x8*)(lds + PG8_SB(b, h) + boff + n * 2048 + k * 1024); } while (0)
; #define PG8_MMA(ai, bj, At, Bt) do { __builtin_amdgcn_s_setprio(1); _Pragma("unroll") for (int m = 0; m < 4; ++m) _Pragma("unroll") for (int n = 0; n < 2; ++n) _Pragma("unroll") for (int k = 0; k < 2; ++k) \
;         acc[ai][bj][m][n] = __builtin_amdgcn_mfma_f32_16x16x32_bf16(Bt[n][k], At[m][k], acc[ai][bj][m][n], 0, 0, 0); __builtin_amdgcn_s_setprio(0); } while (0)
; #define PG8_WAIT_V(n) asm volatile("s_waitcnt vmcnt(" #n ")" ::: "memory")
; #define PG8_WAIT_L(n) asm volatile("s_waitcnt lgkmcnt(" #n ")" ::: "memory")
; #define PG8_BAR __builtin_amdgcn_s_barrier()
; template <class Epi, class Sched, bool ALIGN_EPI = false, bool SP2 = false>
; __device__ __forceinline__ void gemm_phase(PG8_LAS unsigned char* lds, const Gemm g, const Sched& S, const Epi& E) {
;     ...
;         for (int t = 0; t < nt; t += 2) {
;             const bool last = (t == nt - 2);
;             const char* a1 = cA + (size_t)(t + 1) * kstep;
;             const char* a2 = last ? nA : cA + (size_t)(t + 2) * kstep; const char* b2 = last ? nB : cB + (size_t)(t + 2) * kstep;
;             const char* a3 = a2 + kstep; const char* b3 = b2 + kstep;
;     ...
;             PG8_LDB(B0, 1, 0); PG8_LDB(B1, 1, 1); PG8_SCHED; PG8_LDA(At, 1, 0); PG8_STAGE(PG8_SA(0, 1), a2 + hstep, voffA);
;             PG8_WAIT_V(8); PG8_WAIT_L(0); PG8_BAR; PG8_MMA(0, 0, At, B0); PG8_MMA(0, 1, At, B1); PG8_BAR; PG8_SCHED;
;             PG8_LDA(At, 1, 1); PG8_STAGE(PG8_SB(1, 0), b3, voffB); PG8_STAGE(PG8_SB(1, 1), b3 + hstep, voffB); PG8_STAGE(PG8_SA(1, 0), a3, voffA);
;             PG8_WAIT_V(8); PG8_WAIT_L(0); PG8_BAR; PG8_MMA(1, 0, At, B0); PG8_MMA(1, 1, At, B1); PG8_BAR; PG8_SCHED;
	s_add_i32 s24, s47, s23
	v_lshl_add_u64 v[170:171], v[170:171], 0, s[14:15]
	s_mov_b32 m0, s24
	ds_read_b128 v[204:207], v161 offset:49152
	ds_read_b128 v[208:211], v161 offset:50176
	ds_read_b128 v[212:215], v161 offset:51200
	ds_read_b128 v[216:219], v161 offset:52224
	ds_read_b128 v[220:223], v161 offset:53248
	ds_read_b128 v[224:227], v161 offset:54272
	ds_read_b128 v[228:231], v161 offset:55296
	ds_read_b128 v[232:235], v161 offset:56320
	global_load_lds_dwordx4 v[170:171], off
	s_add_i32 m0, s24, 0x2000
	s_add_u32 s24, s58, 0x40080
	v_lshl_add_u64 v[170:171], v[236:237], 0, s[14:15]
	s_addc_u32 s25, s59, 0
	s_add_i32 s47, s50, s23
	global_load_lds_dwordx4 v[170:171], off
	v_lshl_add_u64 v[170:171], s[24:25], 0, v[132:133]
	s_mov_b32 m0, s47
	s_nop 0
	global_load_lds_dwordx4 v[170:171], off
	v_lshl_add_u64 v[170:171], s[24:25], 0, v[140:141]
	s_add_i32 m0, s47, 0x2000
	s_nop 0
	global_load_lds_dwordx4 v[170:171], off
	v_lshl_add_u64 v[170:171], v[238:239], 0, s[14:15]
	s_mov_b32 m0, s65
	s_nop 0
	global_load_lds_dwordx4 v[170:171], off
	v_lshl_add_u64 v[170:171], v[240:241], 0, s[14:15]
	s_mov_b32 m0, s66
	s_nop 0
	global_load_lds_dwordx4 v[170:171], off
	s_waitcnt vmcnt(8)
	s_waitcnt lgkmcnt(0)
	s_barrier
	s_setprio 1
	s_waitcnt lgkmcnt(0)
	v_mfma_f32_16x16x32_bf16 v[60:63], v[146:149], v[204:207], v[60:63]
	v_mfma_f32_16x16x32_bf16 v[56:59], v[154:157], v[204:207], v[56:59]
	v_mfma_f32_16x16x32_bf16 v[44:47], v[146:149], v[212:215], v[44:47]
	v_mfma_f32_16x16x32_bf16 v[40:43], v[154:157], v[212:215], v[40:43]
	v_mfma_f32_16x16x32_bf16 v[28:31], v[146:149], v[220:223], v[28:31]
	v_mfma_f32_16x16x32_bf16 v[24:27], v[154:157], v[220:223], v[24:27]
	v_mfma_f32_16x16x32_bf16 v[12:15], v[146:149], v[228:231], v[12:15]
	v_mfma_f32_16x16x32_bf16 v[8:11], v[154:157], v[228:231], v[8:11]
	v_mfma_f32_16x16x32_bf16 v[60:63], v[150:153], v[208:211], v[60:63]
	v_mfma_f32_16x16x32_bf16 v[56:59], v[162:165], v[208:211], v[56:59]
	v_mfma_f32_16x16x32_bf16 v[44:47], v[150:153], v[216:219], v[44:47]
	v_mfma_f32_16x16x32_bf16 v[40:43], v[162:165], v[216:219], v[40:43]
	v_mfma_f32_16x16x32_bf16 v[28:31], v[150:153], v[224:227], v[28:31]
	v_mfma_f32_16x16x32_bf16 v[24:27], v[162:165], v[224:227], v[24:27]
	v_mfma_f32_16x16x32_bf16 v[12:15], v[150:153], v[232:235], v[12:15]
	v_mfma_f32_16x16x32_bf16 v[8:11], v[162:165], v[232:235], v[8:11]
	s_setprio 0
	s_setprio 1
	v_mfma_f32_16x16x32_bf16 v[52:55], v[166:169], v[204:207], v[52:55]
	v_mfma_f32_16x16x32_bf16 v[48:51], v[196:199], v[204:207], v[48:51]
	v_mfma_f32_16x16x32_bf16 v[36:39], v[166:169], v[212:215], v[36:39]
	v_mfma_f32_16x16x32_bf16 v[32:35], v[196:199], v[212:215], v[32:35]
	v_mfma_f32_16x16x32_bf16 v[20:23], v[166:169], v[220:223], v[20:23]
	v_mfma_f32_16x16x32_bf16 v[16:19], v[196:199], v[220:223], v[16:19]
	v_mfma_f32_16x16x32_bf16 v[4:7], v[166:169], v[228:231], v[4:7]
	v_mfma_f32_16x16x32_bf16 v[0:3], v[196:199], v[228:231], v[0:3]
	v_mfma_f32_16x16x32_bf16 v[52:55], v[192:195], v[208:211], v[52:55]
	v_mfma_f32_16x16x32_bf16 v[48:51], v[200:203], v[208:211], v[48:51]
	v_mfma_f32_16x16x32_bf16 v[36:39], v[192:195], v[216:219], v[36:39]
	v_mfma_f32_16x16x32_bf16 v[32:35], v[200:203], v[216:219], v[32:35]
	v_mfma_f32_16x16x32_bf16 v[20:23], v[192:195], v[224:227], v[20:23]
	v_mfma_f32_16x16x32_bf16 v[16:19], v[200:203], v[224:227], v[16:19]
	v_mfma_f32_16x16x32_bf16 v[4:7], v[192:195], v[232:235], v[4:7]
	v_mfma_f32_16x16x32_bf16 v[0:3], v[200:203], v[232:235], v[0:3]
	s_setprio 0
	s_barrier
	s_add_i32 s45, s45, 2
	s_add_u32 s56, s56, 0x100
	s_addc_u32 s57, s57, 0
	s_add_u32 s22, s22, 0x100
	s_addc_u32 s33, s33, 0
	s_cmp_gt_u32 s45, 13

; #define PG8_STAGE(bufoff, gbase, voff) do { _Pragma("unroll") for (int _i = 0; _i < 2; ++_i) \
;         __builtin_amdgcn_global_load_lds((const unsigned*)((const char*)(gbase) + (voff)[_i]), (PG8_LAS unsigned*)(lds + (bufoff) + ldsw + _i * 8192), 16, 0, 0); } while (0)
; #define PG8_LDA(dst, b, h) do { _Pragma("unroll") for (int m = 0; m < 4; ++m) _Pragma("unroll") for (int k = 0; k < 2; ++k) dst[m][k] = *(const PG8_LAS bf16x8*)(lds + PG8_SA(b, h) + aoff + m * 2048 + k * 1024); } while (0)
; #define PG8_LDB(dst, b, h) do { _Pragma("unroll") for (int n = 0; n < 2; ++n) _Pragma("unroll") for (int k = 0; k < 2; ++k) dst[n][k] = *(const PG8_LAS bf16x8*)(lds + PG8_SB(b, h) + boff + n * 2048 + k * 1024); } while (0)
; template <class Epi, class Sched, bool ALIGN_EPI = false, bool SP2 = false>
; __device__ __forceinline__ void gemm_phase(PG8_LAS unsigned char* lds, const Gemm g, const Sched& S, const Epi& E) {
;     ...
;         const bool has_next = S.next(ui + 1, nxt);
;         const char* nA = has_next ? (const char*)g.A + (size_t)nxt.pm * tstep : cA; const char* nB = has_next ? (const char*)g.Bt + (size_t)nxt.pn * tstep : cB;
;         for (int t = 0; t < nt; t += 2) {
;             const bool last = (t == nt - 2);
;             const char* a1 = cA + (size_t)(t + 1) * kstep;
;             const char* a2 = last ? nA : cA + (size_t)(t + 2) * kstep; const char* b2 = last ? nB : cB + (size_t)(t + 2) * kstep;
;             const char* a3 = a2 + kstep; const char* b3 = b2 + kstep;
;             if (last && has_next) S.a_ready(nxt);
;             if constexpr (SP2) {
;             PG8_LDB(B0, 0, 0); PG8_LDB(B1, 0, 1); PG8_SCHED; PG8_LDA(At, 0, 0); PG8_STAGE(PG8_SA(1, 1), a1 + hstep, voffA);
;             PG8_WAIT_V(8); PG8_WAIT_L(0); PG8_BAR; PG8_MMA(0, 0, At, B0); PG8_MMA(0, 1, At, B1); PG8_BAR; PG8_SCHED;
;             PG8_LDA(At, 0, 1); PG8_STAGE(PG8_SB(0, 0), b2, voffB); PG8_STAGE(PG8_SB(0, 1), b2 + hstep, voffB); PG8_STAGE(PG8_SA(0, 0), a2, voffA);
;             PG8_WAIT_V(8); PG8_WAIT_L(0); PG8_BAR; PG8_MMA(1, 0, At, B0); PG8_MMA(1, 1, At, B1); PG8_BAR; PG8_SCHED;
;     ...
;         for (int a = 0; a < 2; ++a)
; #pragma unroll
;             for (int b = 0; b < 2; ++b)
; #pragma unroll
;                 for (int m = 0; m < 4; ++m)
; #pragma unroll
;                     for (int n = 0; n < 2; ++n) acc[a][b][m][n] = (f32x4){0.f, 0.f, 0.f, 0.f};
.LBB0_698:
	s_add_u32 s48, s48, 0x80
	s_addc_u32 s49, s49, 0
	s_add_u32 s59, s52, 0x100
	s_addc_u32 vcc_lo, s53, 0
	s_mov_b32 s52, 0
	s_add_i32 vcc_hi, s52, 2
	s_add_u32 s24, s48, 0x80
	s_addc_u32 s25, s49, 0
	s_add_i32 s66, 0, 0x10000
	s_cmp_eq_u32 s79, s52
	s_cselect_b32 s53, s39, s25
	s_cselect_b32 s52, s38, s24
	v_add_u32_e32 v132, s66, v147
	s_cselect_b32 s25, s43, vcc_lo
	s_cselect_b32 s24, s42, s59
	s_add_i32 s29, 0, 0x14000
	ds_read_b128 v[156:159], v132
	ds_read_b128 v[162:165], v132 offset:1024
	ds_read_b128 v[166:169], v132 offset:2048
	ds_read_b128 v[192:195], v132 offset:3072
	v_add_u32_e32 v132, s29, v147
	ds_read_b128 v[196:199], v132
	ds_read_b128 v[200:203], v132 offset:1024
	ds_read_b128 v[204:207], v132 offset:2048
	ds_read_b128 v[208:211], v132 offset:3072
	v_lshl_add_u64 v[170:171], s[48:49], 0, v[152:153]
	s_add_i32 m0, s90, 0xc000
	ds_read_b128 v[212:215], v160
	ds_read_b128 v[216:219], v160 offset:1024
	ds_read_b128 v[220:223], v160 offset:2048
	ds_read_b128 v[224:227], v160 offset:3072
	ds_read_b128 v[228:231], v160 offset:4096
	ds_read_b128 v[232:235], v160 offset:5120
	ds_read_b128 v[236:239], v160 offset:6144
	ds_read_b128 v[240:243], v160 offset:7168
	global_load_lds_dwordx4 v[170:171], off
	v_lshl_add_u64 v[170:171], s[48:49], 0, v[154:155]
	s_add_i32 m0, s90, 0xe000
	s_nop 0
	global_load_lds_dwordx4 v[170:171], off
	s_waitcnt vmcnt(8)
	s_waitcnt lgkmcnt(0)
	s_barrier
	s_setprio 1
	s_waitcnt lgkmcnt(0)
	v_mfma_f32_16x16x32_bf16 v[124:127], v[156:159], v[212:215], 0
	v_mfma_f32_16x16x32_bf16 v[120:123], v[166:169], v[212:215], 0
	v_mfma_f32_16x16x32_bf16 v[108:111], v[156:159], v[220:223], 0
	v_mfma_f32_16x16x32_bf16 v[104:107], v[166:169], v[220:223], 0
	v_mfma_f32_16x16x32_bf16 v[92:95], v[156:159], v[228:231], 0
	v_mfma_f32_16x16x32_bf16 v[88:91], v[166:169], v[228:231], 0
	v_mfma_f32_16x16x32_bf16 v[76:79], v[156:159], v[236:239], 0
	v_mfma_f32_16x16x32_bf16 v[72:75], v[166:169], v[236:239], 0
	v_mfma_f32_16x16x32_bf16 v[124:127], v[162:165], v[216:219], v[124:127]
	v_mfma_f32_16x16x32_bf16 v[120:123], v[192:195], v[216:219], v[120:123]
	v_mfma_f32_16x16x32_bf16 v[108:111], v[162:165], v[224:227], v[108:111]
	v_mfma_f32_16x16x32_bf16 v[104:107], v[192:195], v[224:227], v[104:107]
	v_mfma_f32_16x16x32_bf16 v[92:95], v[162:165], v[232:235], v[92:95]
	v_mfma_f32_16x16x32_bf16 v[88:91], v[192:195], v[232:235], v[88:91]
	v_mfma_f32_16x16x32_bf16 v[76:79], v[162:165], v[240:243], v[76:79]
	v_mfma_f32_16x16x32_bf16 v[72:75], v[192:195], v[240:243], v[72:75]
	s_setprio 0
	s_setprio 1
	v_mfma_f32_16x16x32_bf16 v[116:119], v[196:199], v[212:215], 0
	v_mfma_f32_16x16x32_bf16 v[112:115], v[204:207], v[212:215], 0
	v_mfma_f32_16x16x32_bf16 v[100:103], v[196:199], v[220:223], 0
	v_mfma_f32_16x16x32_bf16 v[96:99], v[204:207], v[220:223], 0
	v_mfma_f32_16x16x32_bf16 v[84:87], v[196:199], v[228:231], 0
	v_mfma_f32_16x16x32_bf16 v[80:83], v[204:207], v[228:231], 0
	v_mfma_f32_16x16x32_bf16 v[68:71], v[196:199], v[236:239], 0
	v_mfma_f32_16x16x32_bf16 v[64:67], v[204:207], v[236:239], 0
	v_mfma_f32_16x16x32_bf16 v[116:119], v[200:203], v[216:219], v[116:119]
	v_mfma_f32_16x16x32_bf16 v[112:115], v[208:211], v[216:219], v[112:115]
	v_mfma_f32_16x16x32_bf16 v[100:103], v[200:203], v[224:227], v[100:103]
	v_mfma_f32_16x16x32_bf16 v[96:99], v[208:211], v[224:227], v[96:99]
	v_mfma_f32_16x16x32_bf16 v[84:87], v[200:203], v[232:235], v[84:87]
	v_mfma_f32_16x16x32_bf16 v[80:83], v[208:211], v[232:235], v[80:83]
	v_mfma_f32_16x16x32_bf16 v[68:71], v[200:203], v[240:243], v[68:71]
	v_mfma_f32_16x16x32_bf16 v[64:67], v[208:211], v[240:243], v[64:67]
	s_setprio 0
	s_barrier
	s_add_i32 s66, s66, s89
	v_lshl_add_u64 v[170:171], s[24:25], 0, v[130:131]
	s_mov_b32 m0, s66
	ds_read_b128 v[212:215], v160 offset:16384
	ds_read_b128 v[216:219], v160 offset:17408
	ds_read_b128 v[220:223], v160 offset:18432
	ds_read_b128 v[224:227], v160 offset:19456
	ds_read_b128 v[228:231], v160 offset:20480
	ds_read_b128 v[232:235], v160 offset:21504
	ds_read_b128 v[236:239], v160 offset:22528
	ds_read_b128 v[240:243], v160 offset:23552
	global_load_lds_dwordx4 v[170:171], off
	s_add_i32 m0, s66, 0x2000
	v_lshl_add_u64 v[244:245], s[24:25], 0, v[142:143]
	s_add_u32 s24, s24, s10
	s_addc_u32 s25, s25, 0
	s_add_i32 s29, s29, s89
	global_load_lds_dwordx4 v[244:245], off
	v_lshl_add_u64 v[246:247], s[24:25], 0, v[130:131]
	s_mov_b32 m0, s29
	v_lshl_add_u64 v[248:249], s[24:25], 0, v[142:143]
	global_load_lds_dwordx4 v[246:247], off
	s_add_i32 m0, s29, 0x2000
	v_lshl_add_u64 v[250:251], s[52:53], 0, v[128:129]
	global_load_lds_dwordx4 v[248:249], off
	s_mov_b32 m0, s90
	v_lshl_add_u64 v[252:253], s[52:53], 0, v[140:141]
	global_load_lds_dwordx4 v[250:251], off
	s_mov_b32 m0, s91
	s_nop 0
	global_load_lds_dwordx4 v[252:253], off
	s_waitcnt vmcnt(8)
	s_waitcnt lgkmcnt(0)
	s_barrier
; #define PG8_STAGE(bufoff, gbase, voff) do { _Pragma("unroll") for (int _i = 0; _i < 2; ++_i) \
;         __builtin_amdgcn_global_load_lds((const unsigned*)((const char*)(gbase) + (voff)[_i]), (PG8_LAS unsigned*)(lds + (bufoff) + ldsw + _i * 8192), 16, 0, 0); } while (0)
; #define PG8_LDA(dst, b, h) do { _Pragma("unroll") for (int m = 0; m < 4; ++m) _Pragma("unroll") for (int k = 0; k < 2; ++k) dst[m][k] = *(const PG8_LAS bf16x8*)(lds + PG8_SA(b, h) + aoff + m * 2048 + k * 1024); } while (0)
; #define PG8_LDB(dst, b, h) do { _Pragma("unroll") for (int n = 0; n < 2; ++n) _Pragma("unroll") for (int k = 0; k < 2; ++k) dst[n][k] = *(const PG8_LAS bf16x8*)(lds + PG8_SB(b, h) + boff + n * 2048 + k * 1024); } while (0)
; #define PG8_MMA(ai, bj, At, Bt) do { __builtin_amdgcn_s_setprio(1); _Pragma("unroll") for (int m = 0; m < 4; ++m) _Pragma("unroll") for (int n = 0; n < 2; ++n) _Pragma("unroll") for (int k = 0; k < 2; ++k) \
;         acc[ai][bj][m][n] = __builtin_amdgcn_mfma_f32_16x16x32_bf16(Bt[n][k], At[m][k], acc[ai][bj][m][n], 0, 0, 0); __builtin_amdgcn_s_setprio(0); } while (0)
; #define PG8_WAIT_V(n) asm volatile("s_waitcnt vmcnt(" #n ")" ::: "memory")
; #define PG8_WAIT_L(n) asm volatile("s_waitcnt lgkmcnt(" #n ")" ::: "memory")
; #define PG8_BAR __builtin_amdgcn_s_barrier()
; #define PG8_SCHED __builtin_amdgcn_sched_barrier(0)
; template <class Epi, class Sched, bool ALIGN_EPI = false, bool SP2 = false>
; __device__ __forceinline__ void gemm_phase(PG8_LAS unsigned char* lds, const Gemm g, const Sched& S, const Epi& E) {
;     ...
;             PG8_WAIT_V(8); PG8_WAIT_L(0); PG8_BAR; PG8_MMA(1, 0, At, B0); PG8_MMA(1, 1, At, B1); PG8_BAR; PG8_SCHED;
;             PG8_LDB(B0, 1, 0); PG8_LDB(B1, 1, 1); PG8_SCHED; PG8_LDA(At, 1, 0); PG8_STAGE(PG8_SA(0, 1), a2 + hstep, voffA);
;             PG8_WAIT_V(8); PG8_WAIT_L(0); PG8_BAR; PG8_MMA(0, 0, At, B0); PG8_MMA(0, 1, At, B1); PG8_BAR; PG8_SCHED;
;             PG8_LDA(At, 1, 1); PG8_STAGE(PG8_SB(1, 0), b3, voffB); PG8_STAGE(PG8_SB(1, 1), b3 + hstep, voffB); PG8_STAGE(PG8_SA(1, 0), a3, voffA);
;             PG8_WAIT_V(8); PG8_WAIT_L(0); PG8_BAR; PG8_MMA(1, 0, At, B0); PG8_MMA(1, 1, At, B1); PG8_BAR; PG8_SCHED;
	s_setprio 1
	s_waitcnt lgkmcnt(0)
	v_mfma_f32_16x16x32_bf16 v[60:63], v[156:159], v[212:215], 0
	v_mfma_f32_16x16x32_bf16 v[56:59], v[166:169], v[212:215], 0
	v_mfma_f32_16x16x32_bf16 v[44:47], v[156:159], v[220:223], 0
	v_mfma_f32_16x16x32_bf16 v[40:43], v[166:169], v[220:223], 0
	v_mfma_f32_16x16x32_bf16 v[28:31], v[156:159], v[228:231], 0
	v_mfma_f32_16x16x32_bf16 v[24:27], v[166:169], v[228:231], 0
	v_mfma_f32_16x16x32_bf16 v[12:15], v[156:159], v[236:239], 0
	v_mfma_f32_16x16x32_bf16 v[8:11], v[166:169], v[236:239], 0
	v_mfma_f32_16x16x32_bf16 v[60:63], v[162:165], v[216:219], v[60:63]
	v_mfma_f32_16x16x32_bf16 v[56:59], v[192:195], v[216:219], v[56:59]
	v_mfma_f32_16x16x32_bf16 v[44:47], v[162:165], v[224:227], v[44:47]
	v_mfma_f32_16x16x32_bf16 v[40:43], v[192:195], v[224:227], v[40:43]
	v_mfma_f32_16x16x32_bf16 v[28:31], v[162:165], v[232:235], v[28:31]
	v_mfma_f32_16x16x32_bf16 v[24:27], v[192:195], v[232:235], v[24:27]
	v_mfma_f32_16x16x32_bf16 v[12:15], v[162:165], v[240:243], v[12:15]
	v_mfma_f32_16x16x32_bf16 v[8:11], v[192:195], v[240:243], v[8:11]
	s_setprio 0
	s_setprio 1
	v_mfma_f32_16x16x32_bf16 v[52:55], v[196:199], v[212:215], 0
	v_mfma_f32_16x16x32_bf16 v[48:51], v[204:207], v[212:215], 0
	v_mfma_f32_16x16x32_bf16 v[36:39], v[196:199], v[220:223], 0
	v_mfma_f32_16x16x32_bf16 v[32:35], v[204:207], v[220:223], 0
	v_mfma_f32_16x16x32_bf16 v[20:23], v[196:199], v[228:231], 0
	v_mfma_f32_16x16x32_bf16 v[16:19], v[204:207], v[228:231], 0
	v_mfma_f32_16x16x32_bf16 v[4:7], v[196:199], v[236:239], 0
	v_mfma_f32_16x16x32_bf16 v[0:3], v[204:207], v[236:239], 0
	v_mfma_f32_16x16x32_bf16 v[52:55], v[200:203], v[216:219], v[52:55]
	v_mfma_f32_16x16x32_bf16 v[48:51], v[208:211], v[216:219], v[48:51]
	v_mfma_f32_16x16x32_bf16 v[36:39], v[200:203], v[224:227], v[36:39]
	v_mfma_f32_16x16x32_bf16 v[32:35], v[208:211], v[224:227], v[32:35]
	v_mfma_f32_16x16x32_bf16 v[20:23], v[200:203], v[232:235], v[20:23]
	v_mfma_f32_16x16x32_bf16 v[16:19], v[208:211], v[232:235], v[16:19]
	v_mfma_f32_16x16x32_bf16 v[4:7], v[200:203], v[240:243], v[4:7]
	v_mfma_f32_16x16x32_bf16 v[0:3], v[208:211], v[240:243], v[0:3]
	s_setprio 0
	s_barrier
	s_add_i32 s29, 0, 0x18000
	v_add_u32_e32 v132, s29, v147
	s_add_i32 s66, 0, 0x1c000
	ds_read_b128 v[156:159], v132
	ds_read_b128 v[162:165], v132 offset:1024
	ds_read_b128 v[166:169], v132 offset:2048
	ds_read_b128 v[192:195], v132 offset:3072
	v_add_u32_e32 v132, s66, v147
	ds_read_b128 v[196:199], v132
	ds_read_b128 v[200:203], v132 offset:1024
	ds_read_b128 v[204:207], v132 offset:2048
	ds_read_b128 v[208:211], v132 offset:3072
	s_add_u32 s24, s52, s10
	s_addc_u32 s25, s53, 0
	s_mov_b32 m0, s92
	v_lshl_add_u64 v[184:185], s[24:25], 0, v[128:129]
	ds_read_b128 v[212:215], v160 offset:32768
	ds_read_b128 v[216:219], v160 offset:33792
	ds_read_b128 v[220:223], v160 offset:34816
	ds_read_b128 v[224:227], v160 offset:35840
	ds_read_b128 v[228:231], v160 offset:36864
	ds_read_b128 v[232:235], v160 offset:37888
	ds_read_b128 v[236:239], v160 offset:38912
	ds_read_b128 v[240:243], v160 offset:39936
	global_load_lds_dwordx4 v[184:185], off
	v_lshl_add_u64 v[184:185], s[24:25], 0, v[140:141]
	s_mov_b32 m0, s93
	s_nop 0
	global_load_lds_dwordx4 v[184:185], off
	s_waitcnt vmcnt(8)
	s_waitcnt lgkmcnt(0)
	s_barrier
	s_setprio 1
	s_waitcnt lgkmcnt(0)
	v_mfma_f32_16x16x32_bf16 v[124:127], v[156:159], v[212:215], v[124:127]
	v_mfma_f32_16x16x32_bf16 v[120:123], v[166:169], v[212:215], v[120:123]
	v_mfma_f32_16x16x32_bf16 v[108:111], v[156:159], v[220:223], v[108:111]
	v_mfma_f32_16x16x32_bf16 v[104:107], v[166:169], v[220:223], v[104:107]
	v_mfma_f32_16x16x32_bf16 v[92:95], v[156:159], v[228:231], v[92:95]
	v_mfma_f32_16x16x32_bf16 v[88:91], v[166:169], v[228:231], v[88:91]
	v_mfma_f32_16x16x32_bf16 v[76:79], v[156:159], v[236:239], v[76:79]
	v_mfma_f32_16x16x32_bf16 v[72:75], v[166:169], v[236:239], v[72:75]
	v_mfma_f32_16x16x32_bf16 v[124:127], v[162:165], v[216:219], v[124:127]
	v_mfma_f32_16x16x32_bf16 v[120:123], v[192:195], v[216:219], v[120:123]
	v_mfma_f32_16x16x32_bf16 v[108:111], v[162:165], v[224:227], v[108:111]
	v_mfma_f32_16x16x32_bf16 v[104:107], v[192:195], v[224:227], v[104:107]
	v_mfma_f32_16x16x32_bf16 v[92:95], v[162:165], v[232:235], v[92:95]
	v_mfma_f32_16x16x32_bf16 v[88:91], v[192:195], v[232:235], v[88:91]
	v_mfma_f32_16x16x32_bf16 v[76:79], v[162:165], v[240:243], v[76:79]
	v_mfma_f32_16x16x32_bf16 v[72:75], v[192:195], v[240:243], v[72:75]
	s_setprio 0
	s_setprio 1
	v_mfma_f32_16x16x32_bf16 v[116:119], v[196:199], v[212:215], v[116:119]
	v_mfma_f32_16x16x32_bf16 v[112:115], v[204:207], v[212:215], v[112:115]
	v_mfma_f32_16x16x32_bf16 v[100:103], v[196:199], v[220:223], v[100:103]
	v_mfma_f32_16x16x32_bf16 v[96:99], v[204:207], v[220:223], v[96:99]
	v_mfma_f32_16x16x32_bf16 v[84:87], v[196:199], v[228:231], v[84:87]
	v_mfma_f32_16x16x32_bf16 v[80:83], v[204:207], v[228:231], v[80:83]
	v_mfma_f32_16x16x32_bf16 v[68:71], v[196:199], v[236:239], v[68:71]
	v_mfma_f32_16x16x32_bf16 v[64:67], v[204:207], v[236:239], v[64:67]
	v_mfma_f32_16x16x32_bf16 v[116:119], v[200:203], v[216:219], v[116:119]
	v_mfma_f32_16x16x32_bf16 v[112:115], v[208:211], v[216:219], v[112:115]
	v_mfma_f32_16x16x32_bf16 v[100:103], v[200:203], v[224:227], v[100:103]
	v_mfma_f32_16x16x32_bf16 v[96:99], v[208:211], v[224:227], v[96:99]
	v_mfma_f32_16x16x32_bf16 v[84:87], v[200:203], v[232:235], v[84:87]
	v_mfma_f32_16x16x32_bf16 v[80:83], v[208:211], v[232:235], v[80:83]
	v_mfma_f32_16x16x32_bf16 v[68:71], v[200:203], v[240:243], v[68:71]
	v_mfma_f32_16x16x32_bf16 v[64:67], v[208:211], v[240:243], v[64:67]
	s_setprio 0
	s_barrier
; #define PG8_STAGE(bufoff, gbase, voff) do { _Pragma("unroll") for (int _i = 0; _i < 2; ++_i) \
;         __builtin_amdgcn_global_load_lds((const unsigned*)((const char*)(gbase) + (voff)[_i]), (PG8_LAS unsigned*)(lds + (bufoff) + ldsw + _i * 8192), 16, 0, 0); } while (0)
; #define PG8_LDA(dst, b, h) do { _Pragma("unroll") for (int m = 0; m < 4; ++m) _Pragma("unroll") for (int k = 0; k < 2; ++k) dst[m][k] = *(const PG8_LAS bf16x8*)(lds + PG8_SA(b, h) + aoff + m * 2048 + k * 1024); } while (0)
; #define PG8_LDB(dst, b, h) do { _Pragma("unroll") for (int n = 0; n < 2; ++n) _Pragma("unroll") for (int k = 0; k < 2; ++k) dst[n][k] = *(const PG8_LAS bf16x8*)(lds + PG8_SB(b, h) + boff + n * 2048 + k * 1024); } while (0)
; #define PG8_MMA(ai, bj, At, Bt) do { __builtin_amdgcn_s_setprio(1); _Pragma("unroll") for (int m = 0; m < 4; ++m) _Pragma("unroll") for (int n = 0; n < 2; ++n) _Pragma("unroll") for (int k = 0; k < 2; ++k) \
;         acc[ai][bj][m][n] = __builtin_amdgcn_mfma_f32_16x16x32_bf16(Bt[n][k], At[m][k], acc[ai][bj][m][n], 0, 0, 0); __builtin_amdgcn_s_setprio(0); } while (0)
; #define PG8_WAIT_V(n) asm volatile("s_waitcnt vmcnt(" #n ")" ::: "memory")
; #define PG8_WAIT_L(n) asm volatile("s_waitcnt lgkmcnt(" #n ")" ::: "memory")
; #define PG8_BAR __builtin_amdgcn_s_barrier()
; template <class Epi, class Sched, bool ALIGN_EPI = false, bool SP2 = false>
; __device__ __forceinline__ void gemm_phase(PG8_LAS unsigned char* lds, const Gemm g, const Sched& S, const Epi& E) {
;     ...
;         for (int t = 0; t < nt; t += 2) {
;             const bool last = (t == nt - 2);
;             const char* a1 = cA + (size_t)(t + 1) * kstep;
;             const char* a2 = last ? nA : cA + (size_t)(t + 2) * kstep; const char* b2 = last ? nB : cB + (size_t)(t + 2) * kstep;
;             const char* a3 = a2 + kstep; const char* b3 = b2 + kstep;
;     ...
;             PG8_LDB(B0, 1, 0); PG8_LDB(B1, 1, 1); PG8_SCHED; PG8_LDA(At, 1, 0); PG8_STAGE(PG8_SA(0, 1), a2 + hstep, voffA);
;             PG8_WAIT_V(8); PG8_WAIT_L(0); PG8_BAR; PG8_MMA(0, 0, At, B0); PG8_MMA(0, 1, At, B1); PG8_BAR; PG8_SCHED;
;             PG8_LDA(At, 1, 1); PG8_STAGE(PG8_SB(1, 0), b3, voffB); PG8_STAGE(PG8_SB(1, 1), b3 + hstep, voffB); PG8_STAGE(PG8_SA(1, 0), a3, voffA);
;             PG8_WAIT_V(8); PG8_WAIT_L(0); PG8_BAR; PG8_MMA(1, 0, At, B0); PG8_MMA(1, 1, At, B1); PG8_BAR; PG8_SCHED;
	s_add_i32 s24, s29, s89
	v_lshl_add_u64 v[170:171], v[170:171], 0, s[14:15]
	s_mov_b32 m0, s24
	ds_read_b128 v[212:215], v160 offset:49152
	ds_read_b128 v[216:219], v160 offset:50176
	ds_read_b128 v[220:223], v160 offset:51200
	ds_read_b128 v[224:227], v160 offset:52224
	ds_read_b128 v[228:231], v160 offset:53248
	ds_read_b128 v[232:235], v160 offset:54272
	ds_read_b128 v[236:239], v160 offset:55296
	ds_read_b128 v[240:243], v160 offset:56320
	global_load_lds_dwordx4 v[170:171], off
	v_lshl_add_u64 v[170:171], v[244:245], 0, s[14:15]
	s_add_i32 m0, s24, 0x2000
	s_add_i32 s24, s66, s89
	global_load_lds_dwordx4 v[170:171], off
	v_lshl_add_u64 v[170:171], v[246:247], 0, s[14:15]
	s_mov_b32 m0, s24
	s_nop 0
	global_load_lds_dwordx4 v[170:171], off
	v_lshl_add_u64 v[170:171], v[248:249], 0, s[14:15]
	s_add_i32 m0, s24, 0x2000
	s_nop 0
	global_load_lds_dwordx4 v[170:171], off
	v_lshl_add_u64 v[170:171], v[250:251], 0, s[14:15]
	s_mov_b32 m0, s96
	s_nop 0
	global_load_lds_dwordx4 v[170:171], off
	v_lshl_add_u64 v[170:171], v[252:253], 0, s[14:15]
	s_mov_b32 m0, s97
	s_nop 0
	global_load_lds_dwordx4 v[170:171], off
	s_waitcnt vmcnt(8)
	s_waitcnt lgkmcnt(0)
	s_barrier
	s_setprio 1
	s_waitcnt lgkmcnt(0)
	v_mfma_f32_16x16x32_bf16 v[60:63], v[156:159], v[212:215], v[60:63]
	v_mfma_f32_16x16x32_bf16 v[56:59], v[166:169], v[212:215], v[56:59]
	v_mfma_f32_16x16x32_bf16 v[44:47], v[156:159], v[220:223], v[44:47]
	v_mfma_f32_16x16x32_bf16 v[40:43], v[166:169], v[220:223], v[40:43]
	v_mfma_f32_16x16x32_bf16 v[28:31], v[156:159], v[228:231], v[28:31]
	v_mfma_f32_16x16x32_bf16 v[24:27], v[166:169], v[228:231], v[24:27]
	v_mfma_f32_16x16x32_bf16 v[12:15], v[156:159], v[236:239], v[12:15]
	v_mfma_f32_16x16x32_bf16 v[8:11], v[166:169], v[236:239], v[8:11]
	v_mfma_f32_16x16x32_bf16 v[60:63], v[162:165], v[216:219], v[60:63]
	v_mfma_f32_16x16x32_bf16 v[56:59], v[192:195], v[216:219], v[56:59]
	v_mfma_f32_16x16x32_bf16 v[44:47], v[162:165], v[224:227], v[44:47]
	v_mfma_f32_16x16x32_bf16 v[40:43], v[192:195], v[224:227], v[40:43]
	v_mfma_f32_16x16x32_bf16 v[28:31], v[162:165], v[232:235], v[28:31]
	v_mfma_f32_16x16x32_bf16 v[24:27], v[192:195], v[232:235], v[24:27]
	v_mfma_f32_16x16x32_bf16 v[12:15], v[162:165], v[240:243], v[12:15]
	v_mfma_f32_16x16x32_bf16 v[8:11], v[192:195], v[240:243], v[8:11]
	s_setprio 0
	s_setprio 1
	v_mfma_f32_16x16x32_bf16 v[52:55], v[196:199], v[212:215], v[52:55]
	v_mfma_f32_16x16x32_bf16 v[48:51], v[204:207], v[212:215], v[48:51]
	v_mfma_f32_16x16x32_bf16 v[36:39], v[196:199], v[220:223], v[36:39]
	v_mfma_f32_16x16x32_bf16 v[32:35], v[204:207], v[220:223], v[32:35]
	v_mfma_f32_16x16x32_bf16 v[20:23], v[196:199], v[228:231], v[20:23]
	v_mfma_f32_16x16x32_bf16 v[16:19], v[204:207], v[228:231], v[16:19]
	v_mfma_f32_16x16x32_bf16 v[4:7], v[196:199], v[236:239], v[4:7]
	v_mfma_f32_16x16x32_bf16 v[0:3], v[204:207], v[236:239], v[0:3]
	v_mfma_f32_16x16x32_bf16 v[52:55], v[200:203], v[216:219], v[52:55]
	v_mfma_f32_16x16x32_bf16 v[48:51], v[208:211], v[216:219], v[48:51]
	v_mfma_f32_16x16x32_bf16 v[36:39], v[200:203], v[224:227], v[36:39]
	v_mfma_f32_16x16x32_bf16 v[32:35], v[208:211], v[224:227], v[32:35]
	v_mfma_f32_16x16x32_bf16 v[20:23], v[200:203], v[232:235], v[20:23]
	v_mfma_f32_16x16x32_bf16 v[16:19], v[208:211], v[232:235], v[16:19]
	v_mfma_f32_16x16x32_bf16 v[4:7], v[200:203], v[240:243], v[4:7]
	v_mfma_f32_16x16x32_bf16 v[0:3], v[208:211], v[240:243], v[0:3]
	s_setprio 0
	s_barrier
	s_add_u32 s48, s48, 0x100
	s_addc_u32 s49, s49, 0
	s_add_u32 s59, s59, 0x100
	s_addc_u32 vcc_lo, vcc_lo, 0
	s_cmp_ge_u32 vcc_hi, s78
	s_mov_b32 s52, vcc_hi
